# K-loop MMA segment: s_setprio 1 hoisted before the opening barrier, s_setprio 0 sunk after the closing barrier, redundant lgkmcnt(0) and the mid-run setprio 0/1 pair removed (all 5 GEMM loops)
# speedup vs baseline: 1.0071x; 1.0071x over previous
.LBB0_228:
	ds_read_b128 v[128:131], v179
	ds_read_b128 v[132:135], v179 offset:1024
	ds_read_b128 v[136:139], v179 offset:2048
	ds_read_b128 v[140:143], v179 offset:3072
	ds_read_b128 v[162:165], v180
	ds_read_b128 v[166:169], v180 offset:1024
	ds_read_b128 v[170:173], v180 offset:2048
	ds_read_b128 v[186:189], v180 offset:3072
	s_add_u32 s8, s6, 0x10000
	s_addc_u32 s9, s7, 0
	s_cmp_eq_u32 s92, 12
	s_cselect_b32 s80, s69, s8
	s_cselect_b32 s81, s18, s9
	s_cselect_b32 s12, s77, vcc_lo
	s_cselect_b32 s13, s71, vcc_hi
	s_add_u32 s10, s80, 0x8000
	s_addc_u32 s11, s81, 0
	v_lshl_add_u64 v[174:175], s[6:7], 0, v[154:155]
	s_add_i32 m0, s79, 0xc000
	ds_read_b128 v[190:193], v181
	ds_read_b128 v[194:197], v181 offset:1024
	ds_read_b128 v[198:201], v181 offset:2048
	ds_read_b128 v[202:205], v181 offset:3072
	ds_read_b128 v[206:209], v181 offset:4096
	ds_read_b128 v[210:213], v181 offset:5120
	ds_read_b128 v[214:217], v181 offset:6144
	ds_read_b128 v[218:221], v181 offset:7168
	global_load_lds_dwordx4 v[174:175], off
	v_lshl_add_u64 v[174:175], s[6:7], 0, v[156:157]
	s_add_i32 m0, s79, 0xe000
	s_nop 0
	global_load_lds_dwordx4 v[174:175], off
	s_waitcnt vmcnt(8)
	s_waitcnt lgkmcnt(0)
	s_setprio 1
	s_barrier
	v_mfma_f32_16x16x32_bf16 v[124:127], v[128:131], v[190:193], v[124:127]
	v_mfma_f32_16x16x32_bf16 v[120:123], v[136:139], v[190:193], v[120:123]
	v_mfma_f32_16x16x32_bf16 v[108:111], v[128:131], v[198:201], v[108:111]
	v_mfma_f32_16x16x32_bf16 v[104:107], v[136:139], v[198:201], v[104:107]
	v_mfma_f32_16x16x32_bf16 v[92:95], v[128:131], v[206:209], v[92:95]
	v_mfma_f32_16x16x32_bf16 v[88:91], v[136:139], v[206:209], v[88:91]
	v_mfma_f32_16x16x32_bf16 v[76:79], v[128:131], v[214:217], v[76:79]
	v_mfma_f32_16x16x32_bf16 v[72:75], v[136:139], v[214:217], v[72:75]
	v_mfma_f32_16x16x32_bf16 v[124:127], v[132:135], v[194:197], v[124:127]
	v_mfma_f32_16x16x32_bf16 v[120:123], v[140:143], v[194:197], v[120:123]
	v_mfma_f32_16x16x32_bf16 v[108:111], v[132:135], v[202:205], v[108:111]
	v_mfma_f32_16x16x32_bf16 v[104:107], v[140:143], v[202:205], v[104:107]
	v_mfma_f32_16x16x32_bf16 v[92:95], v[132:135], v[210:213], v[92:95]
	v_mfma_f32_16x16x32_bf16 v[88:91], v[140:143], v[210:213], v[88:91]
	v_mfma_f32_16x16x32_bf16 v[76:79], v[132:135], v[218:221], v[76:79]
	v_mfma_f32_16x16x32_bf16 v[72:75], v[140:143], v[218:221], v[72:75]
	v_mfma_f32_16x16x32_bf16 v[116:119], v[162:165], v[190:193], v[116:119]
	v_mfma_f32_16x16x32_bf16 v[112:115], v[170:173], v[190:193], v[112:115]
	v_mfma_f32_16x16x32_bf16 v[100:103], v[162:165], v[198:201], v[100:103]
	v_mfma_f32_16x16x32_bf16 v[96:99], v[170:173], v[198:201], v[96:99]
	v_mfma_f32_16x16x32_bf16 v[84:87], v[162:165], v[206:209], v[84:87]
	v_mfma_f32_16x16x32_bf16 v[80:83], v[170:173], v[206:209], v[80:83]
	v_mfma_f32_16x16x32_bf16 v[68:71], v[162:165], v[214:217], v[68:71]
	v_mfma_f32_16x16x32_bf16 v[64:67], v[170:173], v[214:217], v[64:67]
	v_mfma_f32_16x16x32_bf16 v[116:119], v[166:169], v[194:197], v[116:119]
	v_mfma_f32_16x16x32_bf16 v[112:115], v[186:189], v[194:197], v[112:115]
	v_mfma_f32_16x16x32_bf16 v[100:103], v[166:169], v[202:205], v[100:103]
	v_mfma_f32_16x16x32_bf16 v[96:99], v[186:189], v[202:205], v[96:99]
	v_mfma_f32_16x16x32_bf16 v[84:87], v[166:169], v[210:213], v[84:87]
	v_mfma_f32_16x16x32_bf16 v[80:83], v[186:189], v[210:213], v[80:83]
	v_mfma_f32_16x16x32_bf16 v[68:71], v[166:169], v[218:221], v[68:71]
	v_mfma_f32_16x16x32_bf16 v[64:67], v[186:189], v[218:221], v[64:67]
	s_barrier
	s_setprio 0
	s_add_i32 s6, s34, s84
	v_lshl_add_u64 v[174:175], s[12:13], 0, v[146:147]
	s_mov_b32 m0, s6
	ds_read_b128 v[190:193], v181 offset:16384
	ds_read_b128 v[194:197], v181 offset:17408
	ds_read_b128 v[198:201], v181 offset:18432
	ds_read_b128 v[202:205], v181 offset:19456
	ds_read_b128 v[206:209], v181 offset:20480
	ds_read_b128 v[210:213], v181 offset:21504
	ds_read_b128 v[214:217], v181 offset:22528
	ds_read_b128 v[218:221], v181 offset:23552
	global_load_lds_dwordx4 v[174:175], off
	s_add_i32 m0, s6, 0x2000
	s_add_u32 s6, s12, 0x40000
	v_lshl_add_u64 v[222:223], s[12:13], 0, v[150:151]
	s_addc_u32 s7, s13, 0
	s_add_i32 s38, s35, s84
	global_load_lds_dwordx4 v[222:223], off
	v_lshl_add_u64 v[224:225], s[6:7], 0, v[146:147]
	s_mov_b32 m0, s38
	s_nop 0
	global_load_lds_dwordx4 v[224:225], off
	v_lshl_add_u64 v[224:225], s[6:7], 0, v[150:151]
	s_add_i32 m0, s38, 0x2000
	s_nop 0
	global_load_lds_dwordx4 v[224:225], off
	v_lshl_add_u64 v[224:225], s[80:81], 0, v[144:145]
	s_mov_b32 m0, s79
	s_nop 0
	global_load_lds_dwordx4 v[224:225], off
	v_lshl_add_u64 v[224:225], s[80:81], 0, v[148:149]
	s_mov_b32 m0, s85
	s_nop 0
	global_load_lds_dwordx4 v[224:225], off
	s_waitcnt vmcnt(8)
	s_waitcnt lgkmcnt(0)
	s_setprio 1
	s_barrier
	v_mfma_f32_16x16x32_bf16 v[60:63], v[128:131], v[190:193], v[60:63]
	v_mfma_f32_16x16x32_bf16 v[56:59], v[136:139], v[190:193], v[56:59]
	v_mfma_f32_16x16x32_bf16 v[44:47], v[128:131], v[198:201], v[44:47]
	v_mfma_f32_16x16x32_bf16 v[40:43], v[136:139], v[198:201], v[40:43]
	v_mfma_f32_16x16x32_bf16 v[28:31], v[128:131], v[206:209], v[28:31]
	v_mfma_f32_16x16x32_bf16 v[24:27], v[136:139], v[206:209], v[24:27]
	v_mfma_f32_16x16x32_bf16 v[12:15], v[128:131], v[214:217], v[12:15]
	v_mfma_f32_16x16x32_bf16 v[8:11], v[136:139], v[214:217], v[8:11]
	v_mfma_f32_16x16x32_bf16 v[60:63], v[132:135], v[194:197], v[60:63]
	v_mfma_f32_16x16x32_bf16 v[56:59], v[140:143], v[194:197], v[56:59]
	v_mfma_f32_16x16x32_bf16 v[44:47], v[132:135], v[202:205], v[44:47]
	v_mfma_f32_16x16x32_bf16 v[40:43], v[140:143], v[202:205], v[40:43]
	v_mfma_f32_16x16x32_bf16 v[28:31], v[132:135], v[210:213], v[28:31]
	v_mfma_f32_16x16x32_bf16 v[24:27], v[140:143], v[210:213], v[24:27]
	v_mfma_f32_16x16x32_bf16 v[12:15], v[132:135], v[218:221], v[12:15]
	v_mfma_f32_16x16x32_bf16 v[8:11], v[140:143], v[218:221], v[8:11]
	v_mfma_f32_16x16x32_bf16 v[52:55], v[162:165], v[190:193], v[52:55]
	v_mfma_f32_16x16x32_bf16 v[48:51], v[170:173], v[190:193], v[48:51]
	v_mfma_f32_16x16x32_bf16 v[36:39], v[162:165], v[198:201], v[36:39]
	v_mfma_f32_16x16x32_bf16 v[32:35], v[170:173], v[198:201], v[32:35]
	v_mfma_f32_16x16x32_bf16 v[20:23], v[162:165], v[206:209], v[20:23]
	v_mfma_f32_16x16x32_bf16 v[16:19], v[170:173], v[206:209], v[16:19]
	v_mfma_f32_16x16x32_bf16 v[4:7], v[162:165], v[214:217], v[4:7]
	v_mfma_f32_16x16x32_bf16 v[0:3], v[170:173], v[214:217], v[0:3]
	v_mfma_f32_16x16x32_bf16 v[52:55], v[166:169], v[194:197], v[52:55]
	v_mfma_f32_16x16x32_bf16 v[48:51], v[186:189], v[194:197], v[48:51]
	v_mfma_f32_16x16x32_bf16 v[36:39], v[166:169], v[202:205], v[36:39]
	v_mfma_f32_16x16x32_bf16 v[32:35], v[186:189], v[202:205], v[32:35]
	v_mfma_f32_16x16x32_bf16 v[20:23], v[166:169], v[210:213], v[20:23]
	v_mfma_f32_16x16x32_bf16 v[16:19], v[186:189], v[210:213], v[16:19]
	v_mfma_f32_16x16x32_bf16 v[4:7], v[166:169], v[218:221], v[4:7]
	v_mfma_f32_16x16x32_bf16 v[0:3], v[186:189], v[218:221], v[0:3]
	s_barrier
	s_setprio 0
	s_add_i32 s38, 0, 0x18000
	s_add_i32 s39, 0, 0x1c000
	v_add_u32_e32 v140, s38, v178
	v_add_u32_e32 v152, s39, v178
	ds_read_b128 v[128:131], v140
	ds_read_b128 v[132:135], v140 offset:1024
	ds_read_b128 v[136:139], v140 offset:2048
	ds_read_b128 v[140:143], v140 offset:3072
	ds_read_b128 v[162:165], v152
	ds_read_b128 v[166:169], v152 offset:1024
	ds_read_b128 v[170:173], v152 offset:2048
	ds_read_b128 v[186:189], v152 offset:3072
	s_add_u32 s6, s80, 0x4000
	s_addc_u32 s7, s81, 0
	s_mov_b32 m0, s86
	v_lshl_add_u64 v[224:225], s[6:7], 0, v[144:145]
	ds_read_b128 v[190:193], v181 offset:32768
	ds_read_b128 v[194:197], v181 offset:33792
	ds_read_b128 v[198:201], v181 offset:34816
	ds_read_b128 v[202:205], v181 offset:35840
	ds_read_b128 v[206:209], v181 offset:36864
	ds_read_b128 v[210:213], v181 offset:37888
	ds_read_b128 v[214:217], v181 offset:38912
	ds_read_b128 v[218:221], v181 offset:39936
	global_load_lds_dwordx4 v[224:225], off
	v_lshl_add_u64 v[224:225], s[6:7], 0, v[148:149]
	s_mov_b32 m0, s87
	s_nop 0
	global_load_lds_dwordx4 v[224:225], off
	s_waitcnt vmcnt(8)
	s_waitcnt lgkmcnt(0)
	s_setprio 1
	s_barrier
	v_mfma_f32_16x16x32_bf16 v[124:127], v[128:131], v[190:193], v[124:127]
	v_mfma_f32_16x16x32_bf16 v[120:123], v[136:139], v[190:193], v[120:123]
	v_mfma_f32_16x16x32_bf16 v[108:111], v[128:131], v[198:201], v[108:111]
	v_mfma_f32_16x16x32_bf16 v[104:107], v[136:139], v[198:201], v[104:107]
	v_mfma_f32_16x16x32_bf16 v[92:95], v[128:131], v[206:209], v[92:95]
	v_mfma_f32_16x16x32_bf16 v[88:91], v[136:139], v[206:209], v[88:91]
	v_mfma_f32_16x16x32_bf16 v[76:79], v[128:131], v[214:217], v[76:79]
	v_mfma_f32_16x16x32_bf16 v[72:75], v[136:139], v[214:217], v[72:75]
	v_mfma_f32_16x16x32_bf16 v[124:127], v[132:135], v[194:197], v[124:127]
	v_mfma_f32_16x16x32_bf16 v[120:123], v[140:143], v[194:197], v[120:123]
	v_mfma_f32_16x16x32_bf16 v[108:111], v[132:135], v[202:205], v[108:111]
	v_mfma_f32_16x16x32_bf16 v[104:107], v[140:143], v[202:205], v[104:107]
	v_mfma_f32_16x16x32_bf16 v[92:95], v[132:135], v[210:213], v[92:95]
	v_mfma_f32_16x16x32_bf16 v[88:91], v[140:143], v[210:213], v[88:91]
	v_mfma_f32_16x16x32_bf16 v[76:79], v[132:135], v[218:221], v[76:79]
	v_mfma_f32_16x16x32_bf16 v[72:75], v[140:143], v[218:221], v[72:75]
	v_mfma_f32_16x16x32_bf16 v[116:119], v[162:165], v[190:193], v[116:119]
	v_mfma_f32_16x16x32_bf16 v[112:115], v[170:173], v[190:193], v[112:115]
	v_mfma_f32_16x16x32_bf16 v[100:103], v[162:165], v[198:201], v[100:103]
	v_mfma_f32_16x16x32_bf16 v[96:99], v[170:173], v[198:201], v[96:99]
	v_mfma_f32_16x16x32_bf16 v[84:87], v[162:165], v[206:209], v[84:87]
	v_mfma_f32_16x16x32_bf16 v[80:83], v[170:173], v[206:209], v[80:83]
	v_mfma_f32_16x16x32_bf16 v[68:71], v[162:165], v[214:217], v[68:71]
	v_mfma_f32_16x16x32_bf16 v[64:67], v[170:173], v[214:217], v[64:67]
	v_mfma_f32_16x16x32_bf16 v[116:119], v[166:169], v[194:197], v[116:119]
	v_mfma_f32_16x16x32_bf16 v[112:115], v[186:189], v[194:197], v[112:115]
	v_mfma_f32_16x16x32_bf16 v[100:103], v[166:169], v[202:205], v[100:103]
	v_mfma_f32_16x16x32_bf16 v[96:99], v[186:189], v[202:205], v[96:99]
	v_mfma_f32_16x16x32_bf16 v[84:87], v[166:169], v[210:213], v[84:87]
	v_mfma_f32_16x16x32_bf16 v[80:83], v[186:189], v[210:213], v[80:83]
	v_mfma_f32_16x16x32_bf16 v[68:71], v[166:169], v[218:221], v[68:71]
	v_mfma_f32_16x16x32_bf16 v[64:67], v[186:189], v[218:221], v[64:67]
	s_barrier
	s_setprio 0
	s_add_i32 s6, s38, s84
	v_lshl_add_u64 v[174:175], v[174:175], 0, s[48:49]
	s_mov_b32 m0, s6
	ds_read_b128 v[190:193], v181 offset:49152
	ds_read_b128 v[194:197], v181 offset:50176
	ds_read_b128 v[198:201], v181 offset:51200
	ds_read_b128 v[202:205], v181 offset:52224
	ds_read_b128 v[206:209], v181 offset:53248
	ds_read_b128 v[210:213], v181 offset:54272
	ds_read_b128 v[214:217], v181 offset:55296
	ds_read_b128 v[218:221], v181 offset:56320
	global_load_lds_dwordx4 v[174:175], off
	s_add_i32 m0, s6, 0x2000
	s_add_u32 s6, s12, 0x40080
	v_lshl_add_u64 v[174:175], v[222:223], 0, s[48:49]
	s_addc_u32 s7, s13, 0
	s_add_i32 s12, s39, s84
	global_load_lds_dwordx4 v[174:175], off
	v_lshl_add_u64 v[174:175], s[6:7], 0, v[146:147]
	s_mov_b32 m0, s12
	s_nop 0
	global_load_lds_dwordx4 v[174:175], off
	v_lshl_add_u64 v[174:175], s[6:7], 0, v[150:151]
	s_add_i32 m0, s12, 0x2000
	s_nop 0
	global_load_lds_dwordx4 v[174:175], off
	v_lshl_add_u64 v[174:175], s[10:11], 0, v[144:145]
	s_mov_b32 m0, s33
	s_nop 0
	global_load_lds_dwordx4 v[174:175], off
	v_lshl_add_u64 v[174:175], s[10:11], 0, v[148:149]
	s_mov_b32 m0, s56
	s_nop 0
	global_load_lds_dwordx4 v[174:175], off
	s_waitcnt vmcnt(8)
	s_waitcnt lgkmcnt(0)
	s_setprio 1
	s_barrier
	v_mfma_f32_16x16x32_bf16 v[60:63], v[128:131], v[190:193], v[60:63]
	v_mfma_f32_16x16x32_bf16 v[56:59], v[136:139], v[190:193], v[56:59]
	v_mfma_f32_16x16x32_bf16 v[44:47], v[128:131], v[198:201], v[44:47]
	v_mfma_f32_16x16x32_bf16 v[40:43], v[136:139], v[198:201], v[40:43]
	v_mfma_f32_16x16x32_bf16 v[28:31], v[128:131], v[206:209], v[28:31]
	v_mfma_f32_16x16x32_bf16 v[24:27], v[136:139], v[206:209], v[24:27]
	v_mfma_f32_16x16x32_bf16 v[12:15], v[128:131], v[214:217], v[12:15]
	v_mfma_f32_16x16x32_bf16 v[8:11], v[136:139], v[214:217], v[8:11]
	v_mfma_f32_16x16x32_bf16 v[60:63], v[132:135], v[194:197], v[60:63]
	v_mfma_f32_16x16x32_bf16 v[56:59], v[140:143], v[194:197], v[56:59]
	v_mfma_f32_16x16x32_bf16 v[44:47], v[132:135], v[202:205], v[44:47]
	v_mfma_f32_16x16x32_bf16 v[40:43], v[140:143], v[202:205], v[40:43]
	v_mfma_f32_16x16x32_bf16 v[28:31], v[132:135], v[210:213], v[28:31]
	v_mfma_f32_16x16x32_bf16 v[24:27], v[140:143], v[210:213], v[24:27]
	v_mfma_f32_16x16x32_bf16 v[12:15], v[132:135], v[218:221], v[12:15]
	v_mfma_f32_16x16x32_bf16 v[8:11], v[140:143], v[218:221], v[8:11]
	v_mfma_f32_16x16x32_bf16 v[52:55], v[162:165], v[190:193], v[52:55]
	v_mfma_f32_16x16x32_bf16 v[48:51], v[170:173], v[190:193], v[48:51]
	v_mfma_f32_16x16x32_bf16 v[36:39], v[162:165], v[198:201], v[36:39]
	v_mfma_f32_16x16x32_bf16 v[32:35], v[170:173], v[198:201], v[32:35]
	v_mfma_f32_16x16x32_bf16 v[20:23], v[162:165], v[206:209], v[20:23]
	v_mfma_f32_16x16x32_bf16 v[16:19], v[170:173], v[206:209], v[16:19]
	v_mfma_f32_16x16x32_bf16 v[4:7], v[162:165], v[214:217], v[4:7]
	v_mfma_f32_16x16x32_bf16 v[0:3], v[170:173], v[214:217], v[0:3]
	v_mfma_f32_16x16x32_bf16 v[52:55], v[166:169], v[194:197], v[52:55]
	v_mfma_f32_16x16x32_bf16 v[48:51], v[186:189], v[194:197], v[48:51]
	v_mfma_f32_16x16x32_bf16 v[36:39], v[166:169], v[202:205], v[36:39]
	v_mfma_f32_16x16x32_bf16 v[32:35], v[186:189], v[202:205], v[32:35]
	v_mfma_f32_16x16x32_bf16 v[20:23], v[166:169], v[210:213], v[20:23]
	v_mfma_f32_16x16x32_bf16 v[16:19], v[186:189], v[210:213], v[16:19]
	v_mfma_f32_16x16x32_bf16 v[4:7], v[166:169], v[218:221], v[4:7]
	v_mfma_f32_16x16x32_bf16 v[0:3], v[186:189], v[218:221], v[0:3]
	s_barrier
	s_setprio 0
	s_add_i32 s92, s92, 2
	s_add_u32 vcc_lo, vcc_lo, 0x100
	s_addc_u32 vcc_hi, vcc_hi, 0
	s_cmp_gt_u32 s92, 13
	s_mov_b64 s[6:7], s[8:9]
	s_cbranch_scc0 .LBB0_228
	s_and_b64 vcc, exec, s[82:83]
	s_cbranch_vccz .LBB0_231
	s_barrier

.LBB0_448:
	v_add_u32_e32 v1, s78, v210
	ds_read_b128 v[132:135], v1
	ds_read_b128 v[136:139], v1 offset:1024
	ds_read_b128 v[140:143], v1 offset:2048
	ds_read_b128 v[144:147], v1 offset:3072
	v_add_u32_e32 v1, s79, v210
	s_add_u32 s48, s38, s46
	ds_read_b128 v[148:151], v1
	ds_read_b128 v[152:155], v1 offset:1024
	ds_read_b128 v[156:159], v1 offset:2048
	ds_read_b128 v[160:163], v1 offset:3072
	s_addc_u32 s49, s39, s47
	s_add_u32 s48, s48, 0x10000
	s_addc_u32 s49, s49, 0
	s_cmp_eq_u32 s46, 0xf0000
	s_cselect_b32 s64, s81, s48
	s_cselect_b32 s65, s21, s49
	s_cselect_b32 s50, s83, s41
	s_cselect_b32 s51, s19, s86
	s_add_u32 s48, s64, 0x8000
	s_addc_u32 s49, s65, 0
	v_lshl_add_u64 v[2:3], v[204:205], 0, s[46:47]
	s_add_i32 m0, s35, 0xc000
	ds_read_b128 v[164:167], v211
	ds_read_b128 v[168:171], v211 offset:1024
	ds_read_b128 v[172:175], v211 offset:2048
	ds_read_b128 v[176:179], v211 offset:3072
	ds_read_b128 v[180:183], v211 offset:4096
	ds_read_b128 v[184:187], v211 offset:5120
	ds_read_b128 v[212:215], v211 offset:6144
	ds_read_b128 v[216:219], v211 offset:7168
	global_load_lds_dwordx4 v[2:3], off
	v_lshl_add_u64 v[2:3], v[206:207], 0, s[46:47]
	s_add_i32 m0, s35, 0xe000
	s_nop 0
	global_load_lds_dwordx4 v[2:3], off
	s_waitcnt vmcnt(8)
	s_waitcnt lgkmcnt(0)
	s_setprio 1
	s_barrier
	v_mfma_f32_16x16x32_bf16 v[128:131], v[132:135], v[164:167], v[128:131]
	v_mfma_f32_16x16x32_bf16 v[124:127], v[140:143], v[164:167], v[124:127]
	v_mfma_f32_16x16x32_bf16 v[112:115], v[132:135], v[172:175], v[112:115]
	v_mfma_f32_16x16x32_bf16 v[108:111], v[140:143], v[172:175], v[108:111]
	v_mfma_f32_16x16x32_bf16 v[96:99], v[132:135], v[180:183], v[96:99]
	v_mfma_f32_16x16x32_bf16 v[92:95], v[140:143], v[180:183], v[92:95]
	v_mfma_f32_16x16x32_bf16 v[80:83], v[132:135], v[212:215], v[80:83]
	v_mfma_f32_16x16x32_bf16 v[76:79], v[140:143], v[212:215], v[76:79]
	v_mfma_f32_16x16x32_bf16 v[128:131], v[136:139], v[168:171], v[128:131]
	v_mfma_f32_16x16x32_bf16 v[124:127], v[144:147], v[168:171], v[124:127]
	v_mfma_f32_16x16x32_bf16 v[112:115], v[136:139], v[176:179], v[112:115]
	v_mfma_f32_16x16x32_bf16 v[108:111], v[144:147], v[176:179], v[108:111]
	v_mfma_f32_16x16x32_bf16 v[96:99], v[136:139], v[184:187], v[96:99]
	v_mfma_f32_16x16x32_bf16 v[92:95], v[144:147], v[184:187], v[92:95]
	v_mfma_f32_16x16x32_bf16 v[80:83], v[136:139], v[216:219], v[80:83]
	v_mfma_f32_16x16x32_bf16 v[76:79], v[144:147], v[216:219], v[76:79]
	v_mfma_f32_16x16x32_bf16 v[120:123], v[148:151], v[164:167], v[120:123]
	v_mfma_f32_16x16x32_bf16 v[116:119], v[156:159], v[164:167], v[116:119]
	v_mfma_f32_16x16x32_bf16 v[104:107], v[148:151], v[172:175], v[104:107]
	v_mfma_f32_16x16x32_bf16 v[100:103], v[156:159], v[172:175], v[100:103]
	v_mfma_f32_16x16x32_bf16 v[88:91], v[148:151], v[180:183], v[88:91]
	v_mfma_f32_16x16x32_bf16 v[84:87], v[156:159], v[180:183], v[84:87]
	v_mfma_f32_16x16x32_bf16 v[72:75], v[148:151], v[212:215], v[72:75]
	v_mfma_f32_16x16x32_bf16 v[68:71], v[156:159], v[212:215], v[68:71]
	v_mfma_f32_16x16x32_bf16 v[120:123], v[152:155], v[168:171], v[120:123]
	v_mfma_f32_16x16x32_bf16 v[116:119], v[160:163], v[168:171], v[116:119]
	v_mfma_f32_16x16x32_bf16 v[104:107], v[152:155], v[176:179], v[104:107]
	v_mfma_f32_16x16x32_bf16 v[100:103], v[160:163], v[176:179], v[100:103]
	v_mfma_f32_16x16x32_bf16 v[88:91], v[152:155], v[184:187], v[88:91]
	v_mfma_f32_16x16x32_bf16 v[84:87], v[160:163], v[184:187], v[84:87]
	v_mfma_f32_16x16x32_bf16 v[72:75], v[152:155], v[216:219], v[72:75]
	v_mfma_f32_16x16x32_bf16 v[68:71], v[160:163], v[216:219], v[68:71]
	s_barrier
	s_setprio 0
	s_add_i32 s88, s78, s34
	v_lshl_add_u64 v[220:221], s[50:51], 0, v[192:193]
	s_mov_b32 m0, s88
	ds_read_b128 v[164:167], v211 offset:16384
	ds_read_b128 v[168:171], v211 offset:17408
	ds_read_b128 v[172:175], v211 offset:18432
	ds_read_b128 v[176:179], v211 offset:19456
	ds_read_b128 v[180:183], v211 offset:20480
	ds_read_b128 v[184:187], v211 offset:21504
	ds_read_b128 v[212:215], v211 offset:22528
	ds_read_b128 v[216:219], v211 offset:23552
	global_load_lds_dwordx4 v[220:221], off
	s_add_i32 m0, s88, 0x2000
	s_add_u32 s88, s50, 0x80000
	v_lshl_add_u64 v[222:223], s[50:51], 0, v[188:189]
	s_addc_u32 s89, s51, 0
	s_add_i32 s90, s79, s34
	global_load_lds_dwordx4 v[222:223], off
	v_lshl_add_u64 v[2:3], s[88:89], 0, v[192:193]
	s_mov_b32 m0, s90
	s_nop 0
	global_load_lds_dwordx4 v[2:3], off
	v_lshl_add_u64 v[2:3], s[88:89], 0, v[188:189]
	s_add_i32 m0, s90, 0x2000
	s_nop 0
	global_load_lds_dwordx4 v[2:3], off
	v_lshl_add_u64 v[2:3], s[64:65], 0, v[194:195]
	s_mov_b32 m0, s35
	s_nop 0
	global_load_lds_dwordx4 v[2:3], off
	v_lshl_add_u64 v[2:3], s[64:65], 0, v[190:191]
	s_mov_b32 m0, s56
	s_nop 0
	global_load_lds_dwordx4 v[2:3], off
	s_waitcnt vmcnt(8)
	s_waitcnt lgkmcnt(0)
	s_setprio 1
	s_barrier
	v_mfma_f32_16x16x32_bf16 v[64:67], v[132:135], v[164:167], v[64:67]
	v_mfma_f32_16x16x32_bf16 v[60:63], v[140:143], v[164:167], v[60:63]
	v_mfma_f32_16x16x32_bf16 v[48:51], v[132:135], v[172:175], v[48:51]
	v_mfma_f32_16x16x32_bf16 v[44:47], v[140:143], v[172:175], v[44:47]
	v_mfma_f32_16x16x32_bf16 v[32:35], v[132:135], v[180:183], v[32:35]
	v_mfma_f32_16x16x32_bf16 v[28:31], v[140:143], v[180:183], v[28:31]
	v_mfma_f32_16x16x32_bf16 v[16:19], v[132:135], v[212:215], v[16:19]
	v_mfma_f32_16x16x32_bf16 v[12:15], v[140:143], v[212:215], v[12:15]
	v_mfma_f32_16x16x32_bf16 v[64:67], v[136:139], v[168:171], v[64:67]
	v_mfma_f32_16x16x32_bf16 v[60:63], v[144:147], v[168:171], v[60:63]
	v_mfma_f32_16x16x32_bf16 v[48:51], v[136:139], v[176:179], v[48:51]
	v_mfma_f32_16x16x32_bf16 v[44:47], v[144:147], v[176:179], v[44:47]
	v_mfma_f32_16x16x32_bf16 v[32:35], v[136:139], v[184:187], v[32:35]
	v_mfma_f32_16x16x32_bf16 v[28:31], v[144:147], v[184:187], v[28:31]
	v_mfma_f32_16x16x32_bf16 v[16:19], v[136:139], v[216:219], v[16:19]
	v_mfma_f32_16x16x32_bf16 v[12:15], v[144:147], v[216:219], v[12:15]
	v_mfma_f32_16x16x32_bf16 v[56:59], v[148:151], v[164:167], v[56:59]
	v_mfma_f32_16x16x32_bf16 v[52:55], v[156:159], v[164:167], v[52:55]
	v_mfma_f32_16x16x32_bf16 v[40:43], v[148:151], v[172:175], v[40:43]
	v_mfma_f32_16x16x32_bf16 v[36:39], v[156:159], v[172:175], v[36:39]
	v_mfma_f32_16x16x32_bf16 v[24:27], v[148:151], v[180:183], v[24:27]
	v_mfma_f32_16x16x32_bf16 v[20:23], v[156:159], v[180:183], v[20:23]
	v_mfma_f32_16x16x32_bf16 v[8:11], v[148:151], v[212:215], v[8:11]
	v_mfma_f32_16x16x32_bf16 v[2:5], v[156:159], v[212:215], v[4:7]
	v_mfma_f32_16x16x32_bf16 v[56:59], v[152:155], v[168:171], v[56:59]
	v_mfma_f32_16x16x32_bf16 v[52:55], v[160:163], v[168:171], v[52:55]
	v_mfma_f32_16x16x32_bf16 v[40:43], v[152:155], v[176:179], v[40:43]
	v_mfma_f32_16x16x32_bf16 v[36:39], v[160:163], v[176:179], v[36:39]
	v_mfma_f32_16x16x32_bf16 v[24:27], v[152:155], v[184:187], v[24:27]
	v_mfma_f32_16x16x32_bf16 v[20:23], v[160:163], v[184:187], v[20:23]
	v_mfma_f32_16x16x32_bf16 v[8:11], v[152:155], v[216:219], v[8:11]
	v_mfma_f32_16x16x32_bf16 v[2:5], v[160:163], v[216:219], v[2:5]
	s_barrier
	s_setprio 0
	s_add_i32 s88, 0, 0x18000
	v_add_u32_e32 v1, s88, v210
	s_add_i32 s89, 0, 0x1c000
	ds_read_b128 v[132:135], v1
	ds_read_b128 v[136:139], v1 offset:1024
	ds_read_b128 v[140:143], v1 offset:2048
	ds_read_b128 v[144:147], v1 offset:3072
	v_add_u32_e32 v1, s89, v210
	ds_read_b128 v[148:151], v1
	ds_read_b128 v[152:155], v1 offset:1024
	ds_read_b128 v[156:159], v1 offset:2048
	ds_read_b128 v[160:163], v1 offset:3072
	s_add_u32 s64, s64, 0x2000
	s_addc_u32 s65, s65, 0
	s_mov_b32 m0, s57
	v_lshl_add_u64 v[6:7], s[64:65], 0, v[194:195]
	ds_read_b128 v[164:167], v211 offset:32768
	ds_read_b128 v[168:171], v211 offset:33792
	ds_read_b128 v[172:175], v211 offset:34816
	ds_read_b128 v[176:179], v211 offset:35840
	ds_read_b128 v[180:183], v211 offset:36864
	ds_read_b128 v[184:187], v211 offset:37888
	ds_read_b128 v[212:215], v211 offset:38912
	ds_read_b128 v[216:219], v211 offset:39936
	global_load_lds_dwordx4 v[6:7], off
	v_lshl_add_u64 v[6:7], s[64:65], 0, v[190:191]
	s_mov_b32 m0, s59
	s_nop 0
	global_load_lds_dwordx4 v[6:7], off
	s_waitcnt vmcnt(8)
	s_waitcnt lgkmcnt(0)
	s_setprio 1
	s_barrier
	v_mfma_f32_16x16x32_bf16 v[128:131], v[132:135], v[164:167], v[128:131]
	v_mfma_f32_16x16x32_bf16 v[124:127], v[140:143], v[164:167], v[124:127]
	v_mfma_f32_16x16x32_bf16 v[112:115], v[132:135], v[172:175], v[112:115]
	v_mfma_f32_16x16x32_bf16 v[108:111], v[140:143], v[172:175], v[108:111]
	v_mfma_f32_16x16x32_bf16 v[96:99], v[132:135], v[180:183], v[96:99]
	v_mfma_f32_16x16x32_bf16 v[92:95], v[140:143], v[180:183], v[92:95]
	v_mfma_f32_16x16x32_bf16 v[80:83], v[132:135], v[212:215], v[80:83]
	v_mfma_f32_16x16x32_bf16 v[76:79], v[140:143], v[212:215], v[76:79]
	v_mfma_f32_16x16x32_bf16 v[128:131], v[136:139], v[168:171], v[128:131]
	v_mfma_f32_16x16x32_bf16 v[124:127], v[144:147], v[168:171], v[124:127]
	v_mfma_f32_16x16x32_bf16 v[112:115], v[136:139], v[176:179], v[112:115]
	v_mfma_f32_16x16x32_bf16 v[108:111], v[144:147], v[176:179], v[108:111]
	v_mfma_f32_16x16x32_bf16 v[96:99], v[136:139], v[184:187], v[96:99]
	v_mfma_f32_16x16x32_bf16 v[92:95], v[144:147], v[184:187], v[92:95]
	v_mfma_f32_16x16x32_bf16 v[80:83], v[136:139], v[216:219], v[80:83]
	v_mfma_f32_16x16x32_bf16 v[76:79], v[144:147], v[216:219], v[76:79]
	v_mfma_f32_16x16x32_bf16 v[120:123], v[148:151], v[164:167], v[120:123]
	v_mfma_f32_16x16x32_bf16 v[116:119], v[156:159], v[164:167], v[116:119]
	v_mfma_f32_16x16x32_bf16 v[104:107], v[148:151], v[172:175], v[104:107]
	v_mfma_f32_16x16x32_bf16 v[100:103], v[156:159], v[172:175], v[100:103]
	v_mfma_f32_16x16x32_bf16 v[88:91], v[148:151], v[180:183], v[88:91]
	v_mfma_f32_16x16x32_bf16 v[84:87], v[156:159], v[180:183], v[84:87]
	v_mfma_f32_16x16x32_bf16 v[72:75], v[148:151], v[212:215], v[72:75]
	v_mfma_f32_16x16x32_bf16 v[68:71], v[156:159], v[212:215], v[68:71]
	v_mfma_f32_16x16x32_bf16 v[120:123], v[152:155], v[168:171], v[120:123]
	v_mfma_f32_16x16x32_bf16 v[116:119], v[160:163], v[168:171], v[116:119]
	v_mfma_f32_16x16x32_bf16 v[104:107], v[152:155], v[176:179], v[104:107]
	v_mfma_f32_16x16x32_bf16 v[100:103], v[160:163], v[176:179], v[100:103]
	v_mfma_f32_16x16x32_bf16 v[88:91], v[152:155], v[184:187], v[88:91]
	v_mfma_f32_16x16x32_bf16 v[84:87], v[160:163], v[184:187], v[84:87]
	v_mfma_f32_16x16x32_bf16 v[72:75], v[152:155], v[216:219], v[72:75]
	v_mfma_f32_16x16x32_bf16 v[68:71], v[160:163], v[216:219], v[68:71]
	s_barrier
	s_setprio 0
	s_add_i32 s64, s88, s34
	v_lshl_add_u64 v[6:7], v[220:221], 0, s[10:11]
	s_mov_b32 m0, s64
	ds_read_b128 v[164:167], v211 offset:49152
	ds_read_b128 v[168:171], v211 offset:50176
	ds_read_b128 v[172:175], v211 offset:51200
	ds_read_b128 v[176:179], v211 offset:52224
	ds_read_b128 v[180:183], v211 offset:53248
	ds_read_b128 v[184:187], v211 offset:54272
	ds_read_b128 v[212:215], v211 offset:55296
	ds_read_b128 v[216:219], v211 offset:56320
	global_load_lds_dwordx4 v[6:7], off
	s_add_i32 m0, s64, 0x2000
	s_add_u32 s50, s50, 0x80080
	v_lshl_add_u64 v[6:7], v[222:223], 0, s[10:11]
	s_addc_u32 s51, s51, 0
	s_add_i32 s64, s89, s34
	global_load_lds_dwordx4 v[6:7], off
	v_lshl_add_u64 v[6:7], s[50:51], 0, v[192:193]
	s_mov_b32 m0, s64
	s_nop 0
	global_load_lds_dwordx4 v[6:7], off
	v_lshl_add_u64 v[6:7], s[50:51], 0, v[188:189]
	s_add_i32 m0, s64, 0x2000
	s_nop 0
	global_load_lds_dwordx4 v[6:7], off
	v_lshl_add_u64 v[6:7], s[48:49], 0, v[194:195]
	s_mov_b32 m0, s74
	s_nop 0
	global_load_lds_dwordx4 v[6:7], off
	v_lshl_add_u64 v[6:7], s[48:49], 0, v[190:191]
	s_mov_b32 m0, s75
	s_nop 0
	global_load_lds_dwordx4 v[6:7], off
	s_waitcnt vmcnt(8)
	s_waitcnt lgkmcnt(0)
	s_setprio 1
	s_barrier
	v_mfma_f32_16x16x32_bf16 v[64:67], v[132:135], v[164:167], v[64:67]
	v_mfma_f32_16x16x32_bf16 v[60:63], v[140:143], v[164:167], v[60:63]
	v_mfma_f32_16x16x32_bf16 v[48:51], v[132:135], v[172:175], v[48:51]
	v_mfma_f32_16x16x32_bf16 v[44:47], v[140:143], v[172:175], v[44:47]
	v_mfma_f32_16x16x32_bf16 v[32:35], v[132:135], v[180:183], v[32:35]
	v_mfma_f32_16x16x32_bf16 v[28:31], v[140:143], v[180:183], v[28:31]
	v_mfma_f32_16x16x32_bf16 v[16:19], v[132:135], v[212:215], v[16:19]
	v_mfma_f32_16x16x32_bf16 v[12:15], v[140:143], v[212:215], v[12:15]
	v_mfma_f32_16x16x32_bf16 v[64:67], v[136:139], v[168:171], v[64:67]
	v_mfma_f32_16x16x32_bf16 v[60:63], v[144:147], v[168:171], v[60:63]
	v_mfma_f32_16x16x32_bf16 v[48:51], v[136:139], v[176:179], v[48:51]
	v_mfma_f32_16x16x32_bf16 v[44:47], v[144:147], v[176:179], v[44:47]
	v_mfma_f32_16x16x32_bf16 v[32:35], v[136:139], v[184:187], v[32:35]
	v_mfma_f32_16x16x32_bf16 v[28:31], v[144:147], v[184:187], v[28:31]
	v_mfma_f32_16x16x32_bf16 v[16:19], v[136:139], v[216:219], v[16:19]
	v_mfma_f32_16x16x32_bf16 v[12:15], v[144:147], v[216:219], v[12:15]
	v_mfma_f32_16x16x32_bf16 v[56:59], v[148:151], v[164:167], v[56:59]
	v_mfma_f32_16x16x32_bf16 v[52:55], v[156:159], v[164:167], v[52:55]
	v_mfma_f32_16x16x32_bf16 v[40:43], v[148:151], v[172:175], v[40:43]
	v_mfma_f32_16x16x32_bf16 v[36:39], v[156:159], v[172:175], v[36:39]
	v_mfma_f32_16x16x32_bf16 v[24:27], v[148:151], v[180:183], v[24:27]
	v_mfma_f32_16x16x32_bf16 v[20:23], v[156:159], v[180:183], v[20:23]
	v_mfma_f32_16x16x32_bf16 v[6:9], v[148:151], v[212:215], v[8:11]
	v_mfma_f32_16x16x32_bf16 v[2:5], v[156:159], v[212:215], v[2:5]
	v_mfma_f32_16x16x32_bf16 v[56:59], v[152:155], v[168:171], v[56:59]
	v_mfma_f32_16x16x32_bf16 v[52:55], v[160:163], v[168:171], v[52:55]
	v_mfma_f32_16x16x32_bf16 v[40:43], v[152:155], v[176:179], v[40:43]
	v_mfma_f32_16x16x32_bf16 v[36:39], v[160:163], v[176:179], v[36:39]
	v_mfma_f32_16x16x32_bf16 v[24:27], v[152:155], v[184:187], v[24:27]
	v_mfma_f32_16x16x32_bf16 v[20:23], v[160:163], v[184:187], v[20:23]
	v_mfma_f32_16x16x32_bf16 v[8:11], v[152:155], v[216:219], v[6:9]
	v_mfma_f32_16x16x32_bf16 v[4:7], v[160:163], v[216:219], v[2:5]
	s_barrier
	s_setprio 0
	s_add_i32 s87, s87, 2
	s_add_u32 s41, s41, 0x100
	s_addc_u32 s86, s86, 0
	s_add_u32 s46, s46, 0x10000
	s_addc_u32 s47, s47, 0
	s_cmp_gt_u32 s87, 29
	s_cbranch_scc1 .LBB0_440

.LBB0_507:
	ds_read_b128 v[128:131], v229
	ds_read_b128 v[132:135], v229 offset:1024
	ds_read_b128 v[136:139], v229 offset:2048
	ds_read_b128 v[140:143], v229 offset:3072
	ds_read_b128 v[144:147], v230
	ds_read_b128 v[148:151], v230 offset:1024
	ds_read_b128 v[152:155], v230 offset:2048
	ds_read_b128 v[156:159], v230 offset:3072
	s_add_u32 s44, s42, 0x10000
	s_addc_u32 s45, s43, 0
	s_cmp_eq_u32 s83, 12
	s_cselect_b32 s50, s21, s44
	s_cselect_b32 s51, s8, s45
	s_cselect_b32 s48, s29, s80
	s_cselect_b32 s49, s27, s81
	s_add_u32 s46, s50, 0x8000
	s_addc_u32 s47, s51, 0
	v_lshl_add_u64 v[208:209], s[42:43], 0, v[200:201]
	s_add_i32 m0, s23, 0xc000
	ds_read_b128 v[160:163], v231
	ds_read_b128 v[164:167], v231 offset:1024
	ds_read_b128 v[168:171], v231 offset:2048
	ds_read_b128 v[172:175], v231 offset:3072
	ds_read_b128 v[176:179], v231 offset:4096
	ds_read_b128 v[180:183], v231 offset:5120
	ds_read_b128 v[184:187], v231 offset:6144
	ds_read_b128 v[188:191], v231 offset:7168
	global_load_lds_dwordx4 v[208:209], off
	v_lshl_add_u64 v[208:209], s[42:43], 0, v[202:203]
	s_add_i32 m0, s23, 0xe000
	s_nop 0
	global_load_lds_dwordx4 v[208:209], off
	s_waitcnt vmcnt(8)
	s_waitcnt lgkmcnt(0)
	s_setprio 1
	s_barrier
	v_mfma_f32_16x16x32_bf16 v[124:127], v[128:131], v[160:163], v[124:127]
	v_mfma_f32_16x16x32_bf16 v[120:123], v[136:139], v[160:163], v[120:123]
	v_mfma_f32_16x16x32_bf16 v[108:111], v[128:131], v[168:171], v[108:111]
	v_mfma_f32_16x16x32_bf16 v[104:107], v[136:139], v[168:171], v[104:107]
	v_mfma_f32_16x16x32_bf16 v[92:95], v[128:131], v[176:179], v[92:95]
	v_mfma_f32_16x16x32_bf16 v[88:91], v[136:139], v[176:179], v[88:91]
	v_mfma_f32_16x16x32_bf16 v[76:79], v[128:131], v[184:187], v[76:79]
	v_mfma_f32_16x16x32_bf16 v[72:75], v[136:139], v[184:187], v[72:75]
	v_mfma_f32_16x16x32_bf16 v[124:127], v[132:135], v[164:167], v[124:127]
	v_mfma_f32_16x16x32_bf16 v[120:123], v[140:143], v[164:167], v[120:123]
	v_mfma_f32_16x16x32_bf16 v[108:111], v[132:135], v[172:175], v[108:111]
	v_mfma_f32_16x16x32_bf16 v[104:107], v[140:143], v[172:175], v[104:107]
	v_mfma_f32_16x16x32_bf16 v[92:95], v[132:135], v[180:183], v[92:95]
	v_mfma_f32_16x16x32_bf16 v[88:91], v[140:143], v[180:183], v[88:91]
	v_mfma_f32_16x16x32_bf16 v[76:79], v[132:135], v[188:191], v[76:79]
	v_mfma_f32_16x16x32_bf16 v[72:75], v[140:143], v[188:191], v[72:75]
	v_mfma_f32_16x16x32_bf16 v[116:119], v[144:147], v[160:163], v[116:119]
	v_mfma_f32_16x16x32_bf16 v[112:115], v[152:155], v[160:163], v[112:115]
	v_mfma_f32_16x16x32_bf16 v[100:103], v[144:147], v[168:171], v[100:103]
	v_mfma_f32_16x16x32_bf16 v[96:99], v[152:155], v[168:171], v[96:99]
	v_mfma_f32_16x16x32_bf16 v[84:87], v[144:147], v[176:179], v[84:87]
	v_mfma_f32_16x16x32_bf16 v[80:83], v[152:155], v[176:179], v[80:83]
	v_mfma_f32_16x16x32_bf16 v[68:71], v[144:147], v[184:187], v[68:71]
	v_mfma_f32_16x16x32_bf16 v[64:67], v[152:155], v[184:187], v[64:67]
	v_mfma_f32_16x16x32_bf16 v[116:119], v[148:151], v[164:167], v[116:119]
	v_mfma_f32_16x16x32_bf16 v[112:115], v[156:159], v[164:167], v[112:115]
	v_mfma_f32_16x16x32_bf16 v[100:103], v[148:151], v[172:175], v[100:103]
	v_mfma_f32_16x16x32_bf16 v[96:99], v[156:159], v[172:175], v[96:99]
	v_mfma_f32_16x16x32_bf16 v[84:87], v[148:151], v[180:183], v[84:87]
	v_mfma_f32_16x16x32_bf16 v[80:83], v[156:159], v[180:183], v[80:83]
	v_mfma_f32_16x16x32_bf16 v[68:71], v[148:151], v[188:191], v[68:71]
	v_mfma_f32_16x16x32_bf16 v[64:67], v[156:159], v[188:191], v[64:67]
	s_barrier
	s_setprio 0
	s_add_i32 s42, s77, s35
	v_lshl_add_u64 v[208:209], s[48:49], 0, v[194:195]
	s_mov_b32 m0, s42
	ds_read_b128 v[160:163], v231 offset:16384
	ds_read_b128 v[164:167], v231 offset:17408
	ds_read_b128 v[168:171], v231 offset:18432
	ds_read_b128 v[172:175], v231 offset:19456
	ds_read_b128 v[176:179], v231 offset:20480
	ds_read_b128 v[180:183], v231 offset:21504
	ds_read_b128 v[184:187], v231 offset:22528
	ds_read_b128 v[188:191], v231 offset:23552
	global_load_lds_dwordx4 v[208:209], off
	s_add_i32 m0, s42, 0x2000
	s_add_u32 s42, s48, 0x40000
	v_lshl_add_u64 v[210:211], s[48:49], 0, v[198:199]
	s_addc_u32 s43, s49, 0
	s_add_i32 s84, s78, s35
	global_load_lds_dwordx4 v[210:211], off
	v_lshl_add_u64 v[212:213], s[42:43], 0, v[194:195]
	s_mov_b32 m0, s84
	s_nop 0
	global_load_lds_dwordx4 v[212:213], off
	v_lshl_add_u64 v[212:213], s[42:43], 0, v[198:199]
	s_add_i32 m0, s84, 0x2000
	s_nop 0
	global_load_lds_dwordx4 v[212:213], off
	v_lshl_add_u64 v[212:213], s[50:51], 0, v[192:193]
	s_mov_b32 m0, s23
	s_nop 0
	global_load_lds_dwordx4 v[212:213], off
	v_lshl_add_u64 v[212:213], s[50:51], 0, v[196:197]
	s_mov_b32 m0, s56
	s_nop 0
	global_load_lds_dwordx4 v[212:213], off
	s_waitcnt vmcnt(8)
	s_waitcnt lgkmcnt(0)
	s_setprio 1
	s_barrier
	v_mfma_f32_16x16x32_bf16 v[60:63], v[128:131], v[160:163], v[60:63]
	v_mfma_f32_16x16x32_bf16 v[56:59], v[136:139], v[160:163], v[56:59]
	v_mfma_f32_16x16x32_bf16 v[44:47], v[128:131], v[168:171], v[44:47]
	v_mfma_f32_16x16x32_bf16 v[40:43], v[136:139], v[168:171], v[40:43]
	v_mfma_f32_16x16x32_bf16 v[28:31], v[128:131], v[176:179], v[28:31]
	v_mfma_f32_16x16x32_bf16 v[24:27], v[136:139], v[176:179], v[24:27]
	v_mfma_f32_16x16x32_bf16 v[12:15], v[128:131], v[184:187], v[12:15]
	v_mfma_f32_16x16x32_bf16 v[8:11], v[136:139], v[184:187], v[8:11]
	v_mfma_f32_16x16x32_bf16 v[60:63], v[132:135], v[164:167], v[60:63]
	v_mfma_f32_16x16x32_bf16 v[56:59], v[140:143], v[164:167], v[56:59]
	v_mfma_f32_16x16x32_bf16 v[44:47], v[132:135], v[172:175], v[44:47]
	v_mfma_f32_16x16x32_bf16 v[40:43], v[140:143], v[172:175], v[40:43]
	v_mfma_f32_16x16x32_bf16 v[28:31], v[132:135], v[180:183], v[28:31]
	v_mfma_f32_16x16x32_bf16 v[24:27], v[140:143], v[180:183], v[24:27]
	v_mfma_f32_16x16x32_bf16 v[12:15], v[132:135], v[188:191], v[12:15]
	v_mfma_f32_16x16x32_bf16 v[8:11], v[140:143], v[188:191], v[8:11]
	v_mfma_f32_16x16x32_bf16 v[52:55], v[144:147], v[160:163], v[52:55]
	v_mfma_f32_16x16x32_bf16 v[48:51], v[152:155], v[160:163], v[48:51]
	v_mfma_f32_16x16x32_bf16 v[36:39], v[144:147], v[168:171], v[36:39]
	v_mfma_f32_16x16x32_bf16 v[32:35], v[152:155], v[168:171], v[32:35]
	v_mfma_f32_16x16x32_bf16 v[20:23], v[144:147], v[176:179], v[20:23]
	v_mfma_f32_16x16x32_bf16 v[16:19], v[152:155], v[176:179], v[16:19]
	v_mfma_f32_16x16x32_bf16 v[4:7], v[144:147], v[184:187], v[4:7]
	v_mfma_f32_16x16x32_bf16 v[0:3], v[152:155], v[184:187], v[0:3]
	v_mfma_f32_16x16x32_bf16 v[52:55], v[148:151], v[164:167], v[52:55]
	v_mfma_f32_16x16x32_bf16 v[48:51], v[156:159], v[164:167], v[48:51]
	v_mfma_f32_16x16x32_bf16 v[36:39], v[148:151], v[172:175], v[36:39]
	v_mfma_f32_16x16x32_bf16 v[32:35], v[156:159], v[172:175], v[32:35]
	v_mfma_f32_16x16x32_bf16 v[20:23], v[148:151], v[180:183], v[20:23]
	v_mfma_f32_16x16x32_bf16 v[16:19], v[156:159], v[180:183], v[16:19]
	v_mfma_f32_16x16x32_bf16 v[4:7], v[148:151], v[188:191], v[4:7]
	v_mfma_f32_16x16x32_bf16 v[0:3], v[156:159], v[188:191], v[0:3]
	s_barrier
	s_setprio 0
	s_add_i32 s84, 0, 0x18000
	s_add_i32 s85, 0, 0x1c000
	v_add_u32_e32 v140, s84, v228
	v_add_u32_e32 v156, s85, v228
	ds_read_b128 v[128:131], v140
	ds_read_b128 v[132:135], v140 offset:1024
	ds_read_b128 v[136:139], v140 offset:2048
	ds_read_b128 v[140:143], v140 offset:3072
	ds_read_b128 v[144:147], v156
	ds_read_b128 v[148:151], v156 offset:1024
	ds_read_b128 v[152:155], v156 offset:2048
	ds_read_b128 v[156:159], v156 offset:3072
	s_add_u32 s42, s50, 0x2000
	s_addc_u32 s43, s51, 0
	s_mov_b32 m0, s57
	v_lshl_add_u64 v[212:213], s[42:43], 0, v[192:193]
	ds_read_b128 v[160:163], v231 offset:32768
	ds_read_b128 v[164:167], v231 offset:33792
	ds_read_b128 v[168:171], v231 offset:34816
	ds_read_b128 v[172:175], v231 offset:35840
	ds_read_b128 v[176:179], v231 offset:36864
	ds_read_b128 v[180:183], v231 offset:37888
	ds_read_b128 v[184:187], v231 offset:38912
	ds_read_b128 v[188:191], v231 offset:39936
	global_load_lds_dwordx4 v[212:213], off
	v_lshl_add_u64 v[212:213], s[42:43], 0, v[196:197]
	s_mov_b32 m0, s59
	s_nop 0
	global_load_lds_dwordx4 v[212:213], off
	s_waitcnt vmcnt(8)
	s_waitcnt lgkmcnt(0)
	s_setprio 1
	s_barrier
	v_mfma_f32_16x16x32_bf16 v[124:127], v[128:131], v[160:163], v[124:127]
	v_mfma_f32_16x16x32_bf16 v[120:123], v[136:139], v[160:163], v[120:123]
	v_mfma_f32_16x16x32_bf16 v[108:111], v[128:131], v[168:171], v[108:111]
	v_mfma_f32_16x16x32_bf16 v[104:107], v[136:139], v[168:171], v[104:107]
	v_mfma_f32_16x16x32_bf16 v[92:95], v[128:131], v[176:179], v[92:95]
	v_mfma_f32_16x16x32_bf16 v[88:91], v[136:139], v[176:179], v[88:91]
	v_mfma_f32_16x16x32_bf16 v[76:79], v[128:131], v[184:187], v[76:79]
	v_mfma_f32_16x16x32_bf16 v[72:75], v[136:139], v[184:187], v[72:75]
	v_mfma_f32_16x16x32_bf16 v[124:127], v[132:135], v[164:167], v[124:127]
	v_mfma_f32_16x16x32_bf16 v[120:123], v[140:143], v[164:167], v[120:123]
	v_mfma_f32_16x16x32_bf16 v[108:111], v[132:135], v[172:175], v[108:111]
	v_mfma_f32_16x16x32_bf16 v[104:107], v[140:143], v[172:175], v[104:107]
	v_mfma_f32_16x16x32_bf16 v[92:95], v[132:135], v[180:183], v[92:95]
	v_mfma_f32_16x16x32_bf16 v[88:91], v[140:143], v[180:183], v[88:91]
	v_mfma_f32_16x16x32_bf16 v[76:79], v[132:135], v[188:191], v[76:79]
	v_mfma_f32_16x16x32_bf16 v[72:75], v[140:143], v[188:191], v[72:75]
	v_mfma_f32_16x16x32_bf16 v[116:119], v[144:147], v[160:163], v[116:119]
	v_mfma_f32_16x16x32_bf16 v[112:115], v[152:155], v[160:163], v[112:115]
	v_mfma_f32_16x16x32_bf16 v[100:103], v[144:147], v[168:171], v[100:103]
	v_mfma_f32_16x16x32_bf16 v[96:99], v[152:155], v[168:171], v[96:99]
	v_mfma_f32_16x16x32_bf16 v[84:87], v[144:147], v[176:179], v[84:87]
	v_mfma_f32_16x16x32_bf16 v[80:83], v[152:155], v[176:179], v[80:83]
	v_mfma_f32_16x16x32_bf16 v[68:71], v[144:147], v[184:187], v[68:71]
	v_mfma_f32_16x16x32_bf16 v[64:67], v[152:155], v[184:187], v[64:67]
	v_mfma_f32_16x16x32_bf16 v[116:119], v[148:151], v[164:167], v[116:119]
	v_mfma_f32_16x16x32_bf16 v[112:115], v[156:159], v[164:167], v[112:115]
	v_mfma_f32_16x16x32_bf16 v[100:103], v[148:151], v[172:175], v[100:103]
	v_mfma_f32_16x16x32_bf16 v[96:99], v[156:159], v[172:175], v[96:99]
	v_mfma_f32_16x16x32_bf16 v[84:87], v[148:151], v[180:183], v[84:87]
	v_mfma_f32_16x16x32_bf16 v[80:83], v[156:159], v[180:183], v[80:83]
	v_mfma_f32_16x16x32_bf16 v[68:71], v[148:151], v[188:191], v[68:71]
	v_mfma_f32_16x16x32_bf16 v[64:67], v[156:159], v[188:191], v[64:67]
	s_barrier
	s_setprio 0
	s_add_i32 s42, s84, s35
	v_lshl_add_u64 v[208:209], v[208:209], 0, s[16:17]
	s_mov_b32 m0, s42
	ds_read_b128 v[160:163], v231 offset:49152
	ds_read_b128 v[164:167], v231 offset:50176
	ds_read_b128 v[168:171], v231 offset:51200
	ds_read_b128 v[172:175], v231 offset:52224
	ds_read_b128 v[176:179], v231 offset:53248
	ds_read_b128 v[180:183], v231 offset:54272
	ds_read_b128 v[184:187], v231 offset:55296
	ds_read_b128 v[188:191], v231 offset:56320
	global_load_lds_dwordx4 v[208:209], off
	s_add_i32 m0, s42, 0x2000
	s_add_u32 s42, s48, 0x40080
	v_lshl_add_u64 v[208:209], v[210:211], 0, s[16:17]
	s_addc_u32 s43, s49, 0
	s_add_i32 s48, s85, s35
	global_load_lds_dwordx4 v[208:209], off
	v_lshl_add_u64 v[208:209], s[42:43], 0, v[194:195]
	s_mov_b32 m0, s48
	s_nop 0
	global_load_lds_dwordx4 v[208:209], off
	v_lshl_add_u64 v[208:209], s[42:43], 0, v[198:199]
	s_add_i32 m0, s48, 0x2000
	s_nop 0
	global_load_lds_dwordx4 v[208:209], off
	v_lshl_add_u64 v[208:209], s[46:47], 0, v[192:193]
	s_mov_b32 m0, s75
	s_nop 0
	global_load_lds_dwordx4 v[208:209], off
	v_lshl_add_u64 v[208:209], s[46:47], 0, v[196:197]
	s_mov_b32 m0, s76
	s_nop 0
	global_load_lds_dwordx4 v[208:209], off
	s_waitcnt vmcnt(8)
	s_waitcnt lgkmcnt(0)
	s_setprio 1
	s_barrier
	v_mfma_f32_16x16x32_bf16 v[60:63], v[128:131], v[160:163], v[60:63]
	v_mfma_f32_16x16x32_bf16 v[56:59], v[136:139], v[160:163], v[56:59]
	v_mfma_f32_16x16x32_bf16 v[44:47], v[128:131], v[168:171], v[44:47]
	v_mfma_f32_16x16x32_bf16 v[40:43], v[136:139], v[168:171], v[40:43]
	v_mfma_f32_16x16x32_bf16 v[28:31], v[128:131], v[176:179], v[28:31]
	v_mfma_f32_16x16x32_bf16 v[24:27], v[136:139], v[176:179], v[24:27]
	v_mfma_f32_16x16x32_bf16 v[12:15], v[128:131], v[184:187], v[12:15]
	v_mfma_f32_16x16x32_bf16 v[8:11], v[136:139], v[184:187], v[8:11]
	v_mfma_f32_16x16x32_bf16 v[60:63], v[132:135], v[164:167], v[60:63]
	v_mfma_f32_16x16x32_bf16 v[56:59], v[140:143], v[164:167], v[56:59]
	v_mfma_f32_16x16x32_bf16 v[44:47], v[132:135], v[172:175], v[44:47]
	v_mfma_f32_16x16x32_bf16 v[40:43], v[140:143], v[172:175], v[40:43]
	v_mfma_f32_16x16x32_bf16 v[28:31], v[132:135], v[180:183], v[28:31]
	v_mfma_f32_16x16x32_bf16 v[24:27], v[140:143], v[180:183], v[24:27]
	v_mfma_f32_16x16x32_bf16 v[12:15], v[132:135], v[188:191], v[12:15]
	v_mfma_f32_16x16x32_bf16 v[8:11], v[140:143], v[188:191], v[8:11]
	v_mfma_f32_16x16x32_bf16 v[52:55], v[144:147], v[160:163], v[52:55]
	v_mfma_f32_16x16x32_bf16 v[48:51], v[152:155], v[160:163], v[48:51]
	v_mfma_f32_16x16x32_bf16 v[36:39], v[144:147], v[168:171], v[36:39]
	v_mfma_f32_16x16x32_bf16 v[32:35], v[152:155], v[168:171], v[32:35]
	v_mfma_f32_16x16x32_bf16 v[20:23], v[144:147], v[176:179], v[20:23]
	v_mfma_f32_16x16x32_bf16 v[16:19], v[152:155], v[176:179], v[16:19]
	v_mfma_f32_16x16x32_bf16 v[4:7], v[144:147], v[184:187], v[4:7]
	v_mfma_f32_16x16x32_bf16 v[0:3], v[152:155], v[184:187], v[0:3]
	v_mfma_f32_16x16x32_bf16 v[52:55], v[148:151], v[164:167], v[52:55]
	v_mfma_f32_16x16x32_bf16 v[48:51], v[156:159], v[164:167], v[48:51]
	v_mfma_f32_16x16x32_bf16 v[36:39], v[148:151], v[172:175], v[36:39]
	v_mfma_f32_16x16x32_bf16 v[32:35], v[156:159], v[172:175], v[32:35]
	v_mfma_f32_16x16x32_bf16 v[20:23], v[148:151], v[180:183], v[20:23]
	v_mfma_f32_16x16x32_bf16 v[16:19], v[156:159], v[180:183], v[16:19]
	v_mfma_f32_16x16x32_bf16 v[4:7], v[148:151], v[188:191], v[4:7]
	v_mfma_f32_16x16x32_bf16 v[0:3], v[156:159], v[188:191], v[0:3]
	s_barrier
	s_setprio 0
	s_add_i32 s83, s83, 2
	s_add_u32 s80, s80, 0x100
	s_addc_u32 s81, s81, 0
	s_cmp_gt_u32 s83, 13
	s_mov_b64 s[42:43], s[44:45]
	s_cbranch_scc0 .LBB0_507
	v_mov_b32_e32 v233, v227
	v_mov_b32_e32 v144, v226
	s_lshl_b32 s8, s22, 8
	s_or_b32 s8, s8, s73
	v_lshlrev_b32_e32 v208, 3, v233
	v_add_u32_e32 v128, s8, v208
	s_lshr_b32 s8, s20, 4
	s_mul_i32 s42, s8, 0x1800
	s_ashr_i32 s43, s42, 31
	s_lshl_b64 s[42:43], s[42:43], 2
	s_add_u32 s42, s69, s42
	v_ashrrev_i32_e32 v129, 31, v128
	v_add_u32_e32 v210, s72, v144
	s_addc_u32 s43, s70, s43
	v_lshlrev_b64 v[212:213], 2, v[128:129]
	v_lshl_add_u32 v216, s20, 8, v210
	v_lshl_add_u64 v[214:215], s[42:43], 0, v[212:213]
	v_ashrrev_i32_e32 v217, 31, v216
	v_add_co_u32_e32 v128, vcc, s65, v214
	v_lshl_add_u64 v[218:219], s[36:37], 0, v[212:213]
	v_lshlrev_b64 v[144:145], 12, v[216:217]
	v_add_u32_e32 v224, 16, v216
	v_lshl_add_u64 v[132:133], v[214:215], 0, s[10:11]
	v_addc_co_u32_e32 v129, vcc, 0, v215, vcc
	v_lshl_add_u64 v[144:145], v[218:219], 0, v[144:145]
	v_ashrrev_i32_e32 v225, 31, v224
	global_load_dwordx4 v[140:143], v[128:129], off
	s_nop 0
	global_load_dwordx4 v[128:131], v[132:133], off offset:528
	global_load_dwordx4 v[136:139], v[132:133], off offset:16
	s_nop 0
	global_load_dwordx4 v[132:135], v[132:133], off offset:512
	s_nop 0
	global_load_dwordx4 v[234:237], v[144:145], off offset:16
	global_load_dwordx4 v[238:241], v[144:145], off
	global_load_dwordx4 v[242:245], v[144:145], off offset:528
	global_load_dwordx4 v[246:249], v[144:145], off offset:512
	v_lshlrev_b64 v[144:145], 12, v[224:225]
	v_add_u32_e32 v222, 32, v216
	v_lshl_add_u64 v[144:145], v[218:219], 0, v[144:145]
	v_ashrrev_i32_e32 v223, 31, v222
	global_load_dwordx4 v[184:187], v[144:145], off offset:16
	global_load_dwordx4 v[188:191], v[144:145], off
	global_load_dwordx4 v[176:179], v[144:145], off offset:528
	global_load_dwordx4 v[180:183], v[144:145], off offset:512
	v_lshlrev_b64 v[144:145], 12, v[222:223]
	v_add_u32_e32 v220, 48, v216
	v_lshl_add_u64 v[144:145], v[218:219], 0, v[144:145]
	v_ashrrev_i32_e32 v221, 31, v220
	global_load_dwordx4 v[168:171], v[144:145], off offset:16
	global_load_dwordx4 v[172:175], v[144:145], off
	global_load_dwordx4 v[160:163], v[144:145], off offset:528
	global_load_dwordx4 v[164:167], v[144:145], off offset:512
	v_lshlrev_b64 v[144:145], 12, v[220:221]
	v_lshl_add_u64 v[148:149], v[218:219], 0, v[144:145]
	global_load_dwordx4 v[152:155], v[148:149], off offset:16
	global_load_dwordx4 v[156:159], v[148:149], off
	global_load_dwordx4 v[144:147], v[148:149], off offset:528
	s_nop 0
	global_load_dwordx4 v[148:151], v[148:149], off offset:512
	v_and_b32_e32 v211, 64, v232
	v_xor_b32_e32 v209, 16, v232
	v_add_u32_e32 v211, 64, v211
	v_cmp_lt_i32_e32 vcc, v209, v211
	v_xor_b32_e32 v250, 32, v232
	s_lshl_b32 s42, s22, 2
	v_cndmask_b32_e32 v209, v232, v209, vcc
	v_cmp_lt_i32_e32 vcc, v250, v211
	v_lshlrev_b32_e32 v209, 2, v209
	s_ashr_i32 s43, s42, 31
	v_cndmask_b32_e32 v211, v232, v250, vcc
	v_lshlrev_b32_e32 v211, 2, v211
	v_cmp_eq_u32_e32 vcc, 0, v233
	s_waitcnt vmcnt(0)
	v_pk_fma_f32 v[126:127], v[126:127], v[142:143], v[240:241]
	v_pk_fma_f32 v[124:125], v[124:125], v[140:141], v[238:239]
	v_pk_fma_f32 v[120:121], v[120:121], v[136:137], v[234:235]
	v_mul_f32_e32 v233, v125, v125
	v_mul_f32_e32 v234, v127, v127
	v_fmac_f32_e32 v233, v124, v124
	v_fmac_f32_e32 v234, v126, v126
	v_add_f32_e32 v233, v233, v234
	v_mul_f32_e32 v234, v121, v121
	v_pk_fma_f32 v[122:123], v[122:123], v[138:139], v[236:237]
	v_fmac_f32_e32 v234, v120, v120
	v_add_f32_e32 v233, v233, v234
	v_mul_f32_e32 v234, v123, v123
	v_fmac_f32_e32 v234, v122, v122
	v_pk_fma_f32 v[118:119], v[118:119], v[134:135], v[248:249]
	v_pk_fma_f32 v[116:117], v[116:117], v[132:133], v[246:247]
	v_add_f32_e32 v233, v234, v233
	v_mul_f32_e32 v234, v117, v117
	v_mul_f32_e32 v235, v119, v119
	v_pk_fma_f32 v[112:113], v[112:113], v[128:129], v[242:243]
	v_fmac_f32_e32 v234, v116, v116
	v_fmac_f32_e32 v235, v118, v118
	v_add_f32_e32 v234, v234, v235
	v_mul_f32_e32 v235, v113, v113
	v_pk_fma_f32 v[114:115], v[114:115], v[130:131], v[244:245]
	v_fmac_f32_e32 v235, v112, v112
	v_add_f32_e32 v234, v234, v235
	v_mul_f32_e32 v235, v115, v115
	v_fmac_f32_e32 v235, v114, v114
	v_add_f32_e32 v234, v235, v234
	v_add_f32_e32 v233, v233, v234
	ds_bpermute_b32 v234, v209, v233
	s_waitcnt lgkmcnt(0)
	v_add_f32_e32 v233, v233, v234
	ds_bpermute_b32 v234, v211, v233
	s_and_saveexec_b64 s[44:45], vcc
	s_cbranch_execz .LBB0_510
	v_lshlrev_b64 v[236:237], 6, v[216:217]
	v_lshl_add_u64 v[236:237], s[12:13], 0, v[236:237]
	v_lshl_add_u64 v[236:237], s[42:43], 2, v[236:237]
	s_lshl_b32 s8, s71, 2
	v_lshl_add_u64 v[236:237], v[236:237], 0, s[8:9]
	s_waitcnt lgkmcnt(0)
	v_add_f32_e32 v217, v233, v234
	global_store_dword v[236:237], v217, off

.LBB0_568:
	ds_read_b128 v[128:131], v167
	ds_read_b128 v[132:135], v167 offset:1024
	ds_read_b128 v[136:139], v167 offset:2048
	ds_read_b128 v[140:143], v167 offset:3072
	ds_read_b128 v[160:163], v168
	ds_read_b128 v[170:173], v168 offset:1024
	ds_read_b128 v[174:177], v168 offset:2048
	ds_read_b128 v[178:181], v168 offset:3072
	s_add_u32 s36, s28, 0x10000
	s_addc_u32 s37, s29, 0
	s_cmp_eq_u32 s76, 12
	s_cselect_b32 s42, s27, s36
	s_cselect_b32 s43, s19, s37
	s_cselect_b32 s40, s73, s74
	s_cselect_b32 s41, s17, s75
	s_add_u32 s38, s42, 0x8000
	s_addc_u32 s39, s43, 0
	v_lshl_add_u64 v[214:215], s[28:29], 0, v[152:153]
	s_add_i32 m0, s44, 0xc000
	ds_read_b128 v[182:185], v169
	ds_read_b128 v[186:189], v169 offset:1024
	ds_read_b128 v[190:193], v169 offset:2048
	ds_read_b128 v[194:197], v169 offset:3072
	ds_read_b128 v[198:201], v169 offset:4096
	ds_read_b128 v[202:205], v169 offset:5120
	ds_read_b128 v[206:209], v169 offset:6144
	ds_read_b128 v[210:213], v169 offset:7168
	global_load_lds_dwordx4 v[214:215], off
	v_lshl_add_u64 v[214:215], s[28:29], 0, v[154:155]
	s_add_i32 m0, s44, 0xe000
	s_nop 0
	global_load_lds_dwordx4 v[214:215], off
	s_waitcnt vmcnt(8)
	s_waitcnt lgkmcnt(0)
	s_setprio 1
	s_barrier
	v_mfma_f32_16x16x32_bf16 v[124:127], v[128:131], v[182:185], v[124:127]
	v_mfma_f32_16x16x32_bf16 v[120:123], v[136:139], v[182:185], v[120:123]
	v_mfma_f32_16x16x32_bf16 v[116:119], v[128:131], v[190:193], v[116:119]
	v_mfma_f32_16x16x32_bf16 v[112:115], v[136:139], v[190:193], v[112:115]
	v_mfma_f32_16x16x32_bf16 v[92:95], v[128:131], v[198:201], v[92:95]
	v_mfma_f32_16x16x32_bf16 v[88:91], v[136:139], v[198:201], v[88:91]
	v_mfma_f32_16x16x32_bf16 v[76:79], v[128:131], v[206:209], v[76:79]
	v_mfma_f32_16x16x32_bf16 v[72:75], v[136:139], v[206:209], v[72:75]
	v_mfma_f32_16x16x32_bf16 v[124:127], v[132:135], v[186:189], v[124:127]
	v_mfma_f32_16x16x32_bf16 v[120:123], v[140:143], v[186:189], v[120:123]
	v_mfma_f32_16x16x32_bf16 v[116:119], v[132:135], v[194:197], v[116:119]
	v_mfma_f32_16x16x32_bf16 v[112:115], v[140:143], v[194:197], v[112:115]
	v_mfma_f32_16x16x32_bf16 v[92:95], v[132:135], v[202:205], v[92:95]
	v_mfma_f32_16x16x32_bf16 v[88:91], v[140:143], v[202:205], v[88:91]
	v_mfma_f32_16x16x32_bf16 v[76:79], v[132:135], v[210:213], v[76:79]
	v_mfma_f32_16x16x32_bf16 v[72:75], v[140:143], v[210:213], v[72:75]
	v_mfma_f32_16x16x32_bf16 v[108:111], v[160:163], v[182:185], v[108:111]
	v_mfma_f32_16x16x32_bf16 v[104:107], v[174:177], v[182:185], v[104:107]
	v_mfma_f32_16x16x32_bf16 v[100:103], v[160:163], v[190:193], v[100:103]
	v_mfma_f32_16x16x32_bf16 v[96:99], v[174:177], v[190:193], v[96:99]
	v_mfma_f32_16x16x32_bf16 v[84:87], v[160:163], v[198:201], v[84:87]
	v_mfma_f32_16x16x32_bf16 v[80:83], v[174:177], v[198:201], v[80:83]
	v_mfma_f32_16x16x32_bf16 v[68:71], v[160:163], v[206:209], v[68:71]
	v_mfma_f32_16x16x32_bf16 v[64:67], v[174:177], v[206:209], v[64:67]
	v_mfma_f32_16x16x32_bf16 v[108:111], v[170:173], v[186:189], v[108:111]
	v_mfma_f32_16x16x32_bf16 v[104:107], v[178:181], v[186:189], v[104:107]
	v_mfma_f32_16x16x32_bf16 v[100:103], v[170:173], v[194:197], v[100:103]
	v_mfma_f32_16x16x32_bf16 v[96:99], v[178:181], v[194:197], v[96:99]
	v_mfma_f32_16x16x32_bf16 v[84:87], v[170:173], v[202:205], v[84:87]
	v_mfma_f32_16x16x32_bf16 v[80:83], v[178:181], v[202:205], v[80:83]
	v_mfma_f32_16x16x32_bf16 v[68:71], v[170:173], v[210:213], v[68:71]
	v_mfma_f32_16x16x32_bf16 v[64:67], v[178:181], v[210:213], v[64:67]
	s_barrier
	s_setprio 0
	s_add_i32 s28, s70, s35
	v_lshl_add_u64 v[214:215], s[40:41], 0, v[148:149]
	s_mov_b32 m0, s28
	ds_read_b128 v[182:185], v169 offset:16384
	ds_read_b128 v[186:189], v169 offset:17408
	ds_read_b128 v[190:193], v169 offset:18432
	ds_read_b128 v[194:197], v169 offset:19456
	ds_read_b128 v[198:201], v169 offset:20480
	ds_read_b128 v[202:205], v169 offset:21504
	ds_read_b128 v[206:209], v169 offset:22528
	ds_read_b128 v[210:213], v169 offset:23552
	global_load_lds_dwordx4 v[214:215], off
	s_add_i32 m0, s28, 0x2000
	s_add_u32 s28, s40, 0x40000
	v_lshl_add_u64 v[216:217], s[40:41], 0, v[144:145]
	s_addc_u32 s29, s41, 0
	s_add_i32 s77, s71, s35
	global_load_lds_dwordx4 v[216:217], off
	v_lshl_add_u64 v[218:219], s[28:29], 0, v[148:149]
	s_mov_b32 m0, s77
	s_nop 0
	global_load_lds_dwordx4 v[218:219], off
	v_lshl_add_u64 v[218:219], s[28:29], 0, v[144:145]
	s_add_i32 m0, s77, 0x2000
	s_nop 0
	global_load_lds_dwordx4 v[218:219], off
	v_lshl_add_u64 v[218:219], s[42:43], 0, v[150:151]
	s_mov_b32 m0, s44
	s_nop 0
	global_load_lds_dwordx4 v[218:219], off
	v_lshl_add_u64 v[218:219], s[42:43], 0, v[146:147]
	s_mov_b32 m0, s45
	s_nop 0
	global_load_lds_dwordx4 v[218:219], off
	s_waitcnt vmcnt(8)
	s_waitcnt lgkmcnt(0)
	s_setprio 1
	s_barrier
	v_mfma_f32_16x16x32_bf16 v[60:63], v[128:131], v[182:185], v[60:63]
	v_mfma_f32_16x16x32_bf16 v[56:59], v[136:139], v[182:185], v[56:59]
	v_mfma_f32_16x16x32_bf16 v[44:47], v[128:131], v[190:193], v[44:47]
	v_mfma_f32_16x16x32_bf16 v[40:43], v[136:139], v[190:193], v[40:43]
	v_mfma_f32_16x16x32_bf16 v[28:31], v[128:131], v[198:201], v[28:31]
	v_mfma_f32_16x16x32_bf16 v[24:27], v[136:139], v[198:201], v[24:27]
	v_mfma_f32_16x16x32_bf16 v[12:15], v[128:131], v[206:209], v[12:15]
	v_mfma_f32_16x16x32_bf16 v[8:11], v[136:139], v[206:209], v[8:11]
	v_mfma_f32_16x16x32_bf16 v[60:63], v[132:135], v[186:189], v[60:63]
	v_mfma_f32_16x16x32_bf16 v[56:59], v[140:143], v[186:189], v[56:59]
	v_mfma_f32_16x16x32_bf16 v[44:47], v[132:135], v[194:197], v[44:47]
	v_mfma_f32_16x16x32_bf16 v[40:43], v[140:143], v[194:197], v[40:43]
	v_mfma_f32_16x16x32_bf16 v[28:31], v[132:135], v[202:205], v[28:31]
	v_mfma_f32_16x16x32_bf16 v[24:27], v[140:143], v[202:205], v[24:27]
	v_mfma_f32_16x16x32_bf16 v[12:15], v[132:135], v[210:213], v[12:15]
	v_mfma_f32_16x16x32_bf16 v[8:11], v[140:143], v[210:213], v[8:11]
	v_mfma_f32_16x16x32_bf16 v[52:55], v[160:163], v[182:185], v[52:55]
	v_mfma_f32_16x16x32_bf16 v[48:51], v[174:177], v[182:185], v[48:51]
	v_mfma_f32_16x16x32_bf16 v[36:39], v[160:163], v[190:193], v[36:39]
	v_mfma_f32_16x16x32_bf16 v[32:35], v[174:177], v[190:193], v[32:35]
	v_mfma_f32_16x16x32_bf16 v[20:23], v[160:163], v[198:201], v[20:23]
	v_mfma_f32_16x16x32_bf16 v[16:19], v[174:177], v[198:201], v[16:19]
	v_mfma_f32_16x16x32_bf16 v[4:7], v[160:163], v[206:209], v[4:7]
	v_mfma_f32_16x16x32_bf16 v[0:3], v[174:177], v[206:209], v[0:3]
	v_mfma_f32_16x16x32_bf16 v[52:55], v[170:173], v[186:189], v[52:55]
	v_mfma_f32_16x16x32_bf16 v[48:51], v[178:181], v[186:189], v[48:51]
	v_mfma_f32_16x16x32_bf16 v[36:39], v[170:173], v[194:197], v[36:39]
	v_mfma_f32_16x16x32_bf16 v[32:35], v[178:181], v[194:197], v[32:35]
	v_mfma_f32_16x16x32_bf16 v[20:23], v[170:173], v[202:205], v[20:23]
	v_mfma_f32_16x16x32_bf16 v[16:19], v[178:181], v[202:205], v[16:19]
	v_mfma_f32_16x16x32_bf16 v[4:7], v[170:173], v[210:213], v[4:7]
	v_mfma_f32_16x16x32_bf16 v[0:3], v[178:181], v[210:213], v[0:3]
	s_barrier
	s_setprio 0
	s_add_i32 s77, 0, 0x18000
	s_add_i32 s78, 0, 0x1c000
	v_add_u32_e32 v140, s77, v166
	v_add_u32_e32 v178, s78, v166
	ds_read_b128 v[128:131], v140
	ds_read_b128 v[132:135], v140 offset:1024
	ds_read_b128 v[136:139], v140 offset:2048
	ds_read_b128 v[140:143], v140 offset:3072
	ds_read_b128 v[160:163], v178
	ds_read_b128 v[170:173], v178 offset:1024
	ds_read_b128 v[174:177], v178 offset:2048
	ds_read_b128 v[178:181], v178 offset:3072
	s_add_u32 s28, s42, 0x2000
	s_addc_u32 s29, s43, 0
	s_mov_b32 m0, s46
	v_lshl_add_u64 v[218:219], s[28:29], 0, v[150:151]
	ds_read_b128 v[182:185], v169 offset:32768
	ds_read_b128 v[186:189], v169 offset:33792
	ds_read_b128 v[190:193], v169 offset:34816
	ds_read_b128 v[194:197], v169 offset:35840
	ds_read_b128 v[198:201], v169 offset:36864
	ds_read_b128 v[202:205], v169 offset:37888
	ds_read_b128 v[206:209], v169 offset:38912
	ds_read_b128 v[210:213], v169 offset:39936
	global_load_lds_dwordx4 v[218:219], off
	v_lshl_add_u64 v[218:219], s[28:29], 0, v[146:147]
	s_mov_b32 m0, s47
	s_nop 0
	global_load_lds_dwordx4 v[218:219], off
	s_waitcnt vmcnt(8)
	s_waitcnt lgkmcnt(0)
	s_setprio 1
	s_barrier
	v_mfma_f32_16x16x32_bf16 v[124:127], v[128:131], v[182:185], v[124:127]
	v_mfma_f32_16x16x32_bf16 v[120:123], v[136:139], v[182:185], v[120:123]
	v_mfma_f32_16x16x32_bf16 v[116:119], v[128:131], v[190:193], v[116:119]
	v_mfma_f32_16x16x32_bf16 v[112:115], v[136:139], v[190:193], v[112:115]
	v_mfma_f32_16x16x32_bf16 v[92:95], v[128:131], v[198:201], v[92:95]
	v_mfma_f32_16x16x32_bf16 v[88:91], v[136:139], v[198:201], v[88:91]
	v_mfma_f32_16x16x32_bf16 v[76:79], v[128:131], v[206:209], v[76:79]
	v_mfma_f32_16x16x32_bf16 v[72:75], v[136:139], v[206:209], v[72:75]
	v_mfma_f32_16x16x32_bf16 v[124:127], v[132:135], v[186:189], v[124:127]
	v_mfma_f32_16x16x32_bf16 v[120:123], v[140:143], v[186:189], v[120:123]
	v_mfma_f32_16x16x32_bf16 v[116:119], v[132:135], v[194:197], v[116:119]
	v_mfma_f32_16x16x32_bf16 v[112:115], v[140:143], v[194:197], v[112:115]
	v_mfma_f32_16x16x32_bf16 v[92:95], v[132:135], v[202:205], v[92:95]
	v_mfma_f32_16x16x32_bf16 v[88:91], v[140:143], v[202:205], v[88:91]
	v_mfma_f32_16x16x32_bf16 v[76:79], v[132:135], v[210:213], v[76:79]
	v_mfma_f32_16x16x32_bf16 v[72:75], v[140:143], v[210:213], v[72:75]
	v_mfma_f32_16x16x32_bf16 v[108:111], v[160:163], v[182:185], v[108:111]
	v_mfma_f32_16x16x32_bf16 v[104:107], v[174:177], v[182:185], v[104:107]
	v_mfma_f32_16x16x32_bf16 v[100:103], v[160:163], v[190:193], v[100:103]
	v_mfma_f32_16x16x32_bf16 v[96:99], v[174:177], v[190:193], v[96:99]
	v_mfma_f32_16x16x32_bf16 v[84:87], v[160:163], v[198:201], v[84:87]
	v_mfma_f32_16x16x32_bf16 v[80:83], v[174:177], v[198:201], v[80:83]
	v_mfma_f32_16x16x32_bf16 v[68:71], v[160:163], v[206:209], v[68:71]
	v_mfma_f32_16x16x32_bf16 v[64:67], v[174:177], v[206:209], v[64:67]
	v_mfma_f32_16x16x32_bf16 v[108:111], v[170:173], v[186:189], v[108:111]
	v_mfma_f32_16x16x32_bf16 v[104:107], v[178:181], v[186:189], v[104:107]
	v_mfma_f32_16x16x32_bf16 v[100:103], v[170:173], v[194:197], v[100:103]
	v_mfma_f32_16x16x32_bf16 v[96:99], v[178:181], v[194:197], v[96:99]
	v_mfma_f32_16x16x32_bf16 v[84:87], v[170:173], v[202:205], v[84:87]
	v_mfma_f32_16x16x32_bf16 v[80:83], v[178:181], v[202:205], v[80:83]
	v_mfma_f32_16x16x32_bf16 v[68:71], v[170:173], v[210:213], v[68:71]
	v_mfma_f32_16x16x32_bf16 v[64:67], v[178:181], v[210:213], v[64:67]
	s_barrier
	s_setprio 0
	s_add_i32 s28, s77, s35
	v_lshl_add_u64 v[214:215], v[214:215], 0, s[12:13]
	s_mov_b32 m0, s28
	ds_read_b128 v[182:185], v169 offset:49152
	ds_read_b128 v[186:189], v169 offset:50176
	ds_read_b128 v[190:193], v169 offset:51200
	ds_read_b128 v[194:197], v169 offset:52224
	ds_read_b128 v[198:201], v169 offset:53248
	ds_read_b128 v[202:205], v169 offset:54272
	ds_read_b128 v[206:209], v169 offset:55296
	ds_read_b128 v[210:213], v169 offset:56320
	global_load_lds_dwordx4 v[214:215], off
	s_add_i32 m0, s28, 0x2000
	s_add_u32 s28, s40, 0x40080
	v_lshl_add_u64 v[214:215], v[216:217], 0, s[12:13]
	s_addc_u32 s29, s41, 0
	s_add_i32 s40, s78, s35
	global_load_lds_dwordx4 v[214:215], off
	v_lshl_add_u64 v[214:215], s[28:29], 0, v[148:149]
	s_mov_b32 m0, s40
	s_nop 0
	global_load_lds_dwordx4 v[214:215], off
	v_lshl_add_u64 v[214:215], s[28:29], 0, v[144:145]
	s_add_i32 m0, s40, 0x2000
	s_nop 0
	global_load_lds_dwordx4 v[214:215], off
	v_lshl_add_u64 v[214:215], s[38:39], 0, v[150:151]
	s_mov_b32 m0, s68
	s_nop 0
	global_load_lds_dwordx4 v[214:215], off
	v_lshl_add_u64 v[214:215], s[38:39], 0, v[146:147]
	s_mov_b32 m0, s69
	s_nop 0
	global_load_lds_dwordx4 v[214:215], off
	s_waitcnt vmcnt(8)
	s_waitcnt lgkmcnt(0)
	s_setprio 1
	s_barrier
	v_mfma_f32_16x16x32_bf16 v[60:63], v[128:131], v[182:185], v[60:63]
	v_mfma_f32_16x16x32_bf16 v[56:59], v[136:139], v[182:185], v[56:59]
	v_mfma_f32_16x16x32_bf16 v[44:47], v[128:131], v[190:193], v[44:47]
	v_mfma_f32_16x16x32_bf16 v[40:43], v[136:139], v[190:193], v[40:43]
	v_mfma_f32_16x16x32_bf16 v[28:31], v[128:131], v[198:201], v[28:31]
	v_mfma_f32_16x16x32_bf16 v[24:27], v[136:139], v[198:201], v[24:27]
	v_mfma_f32_16x16x32_bf16 v[12:15], v[128:131], v[206:209], v[12:15]
	v_mfma_f32_16x16x32_bf16 v[8:11], v[136:139], v[206:209], v[8:11]
	v_mfma_f32_16x16x32_bf16 v[60:63], v[132:135], v[186:189], v[60:63]
	v_mfma_f32_16x16x32_bf16 v[56:59], v[140:143], v[186:189], v[56:59]
	v_mfma_f32_16x16x32_bf16 v[44:47], v[132:135], v[194:197], v[44:47]
	v_mfma_f32_16x16x32_bf16 v[40:43], v[140:143], v[194:197], v[40:43]
	v_mfma_f32_16x16x32_bf16 v[28:31], v[132:135], v[202:205], v[28:31]
	v_mfma_f32_16x16x32_bf16 v[24:27], v[140:143], v[202:205], v[24:27]
	v_mfma_f32_16x16x32_bf16 v[12:15], v[132:135], v[210:213], v[12:15]
	v_mfma_f32_16x16x32_bf16 v[8:11], v[140:143], v[210:213], v[8:11]
	v_mfma_f32_16x16x32_bf16 v[52:55], v[160:163], v[182:185], v[52:55]
	v_mfma_f32_16x16x32_bf16 v[48:51], v[174:177], v[182:185], v[48:51]
	v_mfma_f32_16x16x32_bf16 v[36:39], v[160:163], v[190:193], v[36:39]
	v_mfma_f32_16x16x32_bf16 v[32:35], v[174:177], v[190:193], v[32:35]
	v_mfma_f32_16x16x32_bf16 v[20:23], v[160:163], v[198:201], v[20:23]
	v_mfma_f32_16x16x32_bf16 v[16:19], v[174:177], v[198:201], v[16:19]
	v_mfma_f32_16x16x32_bf16 v[4:7], v[160:163], v[206:209], v[4:7]
	v_mfma_f32_16x16x32_bf16 v[0:3], v[174:177], v[206:209], v[0:3]
	v_mfma_f32_16x16x32_bf16 v[52:55], v[170:173], v[186:189], v[52:55]
	v_mfma_f32_16x16x32_bf16 v[48:51], v[178:181], v[186:189], v[48:51]
	v_mfma_f32_16x16x32_bf16 v[36:39], v[170:173], v[194:197], v[36:39]
	v_mfma_f32_16x16x32_bf16 v[32:35], v[178:181], v[194:197], v[32:35]
	v_mfma_f32_16x16x32_bf16 v[20:23], v[170:173], v[202:205], v[20:23]
	v_mfma_f32_16x16x32_bf16 v[16:19], v[178:181], v[202:205], v[16:19]
	v_mfma_f32_16x16x32_bf16 v[4:7], v[170:173], v[210:213], v[4:7]
	v_mfma_f32_16x16x32_bf16 v[0:3], v[178:181], v[210:213], v[0:3]
	s_barrier
	s_setprio 0
	s_add_i32 s76, s76, 2
	s_add_u32 s74, s74, 0x100
	s_addc_u32 s75, s75, 0
	s_cmp_gt_u32 s76, 13
	s_mov_b64 s[28:29], s[36:37]
	s_cbranch_scc0 .LBB0_568
	s_and_b64 vcc, exec, s[10:11]
	s_cbranch_vccz .LBB0_571
	s_barrier

.LBB0_615:
	v_add_u32_e32 v151, s51, v149
	ds_read_b128 v[152:155], v151
	ds_read_b128 v[156:159], v151 offset:1024
	ds_read_b128 v[160:163], v151 offset:2048
	ds_read_b128 v[164:167], v151 offset:3072
	v_add_u32_e32 v151, s56, v149
	ds_read_b128 v[168:171], v151
	ds_read_b128 v[172:175], v151 offset:1024
	ds_read_b128 v[176:179], v151 offset:2048
	ds_read_b128 v[180:183], v151 offset:3072
	s_add_u32 s38, s12, s36
	s_addc_u32 s39, s13, s37
	s_cmp_eq_u32 s63, 60
	s_cselect_b32 s42, s59, s38
	s_cselect_b32 s43, s23, s39
	s_cselect_b32 s40, s60, s61
	s_cselect_b32 s41, s21, s62
	s_add_u32 s38, s42, 0x8000
	s_addc_u32 s39, s43, 0
	v_lshl_add_u64 v[216:217], s[12:13], 0, v[146:147]
	s_add_i32 m0, s44, 0xc000
	ds_read_b128 v[184:187], v150
	ds_read_b128 v[188:191], v150 offset:1024
	ds_read_b128 v[192:195], v150 offset:2048
	ds_read_b128 v[196:199], v150 offset:3072
	ds_read_b128 v[200:203], v150 offset:4096
	ds_read_b128 v[204:207], v150 offset:5120
	ds_read_b128 v[208:211], v150 offset:6144
	ds_read_b128 v[212:215], v150 offset:7168
	global_load_lds_dwordx4 v[216:217], off
	v_lshl_add_u64 v[216:217], s[12:13], 0, v[144:145]
	s_add_i32 m0, s44, 0xe000
	s_nop 0
	global_load_lds_dwordx4 v[216:217], off
	s_waitcnt vmcnt(8)
	s_waitcnt lgkmcnt(0)
	s_setprio 1
	s_barrier
	v_mfma_f32_16x16x32_bf16 v[124:127], v[152:155], v[184:187], v[124:127]
	v_mfma_f32_16x16x32_bf16 v[120:123], v[160:163], v[184:187], v[120:123]
	v_mfma_f32_16x16x32_bf16 v[108:111], v[152:155], v[192:195], v[108:111]
	v_mfma_f32_16x16x32_bf16 v[104:107], v[160:163], v[192:195], v[104:107]
	v_mfma_f32_16x16x32_bf16 v[92:95], v[152:155], v[200:203], v[92:95]
	v_mfma_f32_16x16x32_bf16 v[88:91], v[160:163], v[200:203], v[88:91]
	v_mfma_f32_16x16x32_bf16 v[76:79], v[152:155], v[208:211], v[76:79]
	v_mfma_f32_16x16x32_bf16 v[72:75], v[160:163], v[208:211], v[72:75]
	v_mfma_f32_16x16x32_bf16 v[124:127], v[156:159], v[188:191], v[124:127]
	v_mfma_f32_16x16x32_bf16 v[120:123], v[164:167], v[188:191], v[120:123]
	v_mfma_f32_16x16x32_bf16 v[108:111], v[156:159], v[196:199], v[108:111]
	v_mfma_f32_16x16x32_bf16 v[104:107], v[164:167], v[196:199], v[104:107]
	v_mfma_f32_16x16x32_bf16 v[92:95], v[156:159], v[204:207], v[92:95]
	v_mfma_f32_16x16x32_bf16 v[88:91], v[164:167], v[204:207], v[88:91]
	v_mfma_f32_16x16x32_bf16 v[76:79], v[156:159], v[212:215], v[76:79]
	v_mfma_f32_16x16x32_bf16 v[72:75], v[164:167], v[212:215], v[72:75]
	v_mfma_f32_16x16x32_bf16 v[116:119], v[168:171], v[184:187], v[116:119]
	v_mfma_f32_16x16x32_bf16 v[112:115], v[176:179], v[184:187], v[112:115]
	v_mfma_f32_16x16x32_bf16 v[100:103], v[168:171], v[192:195], v[100:103]
	v_mfma_f32_16x16x32_bf16 v[96:99], v[176:179], v[192:195], v[96:99]
	v_mfma_f32_16x16x32_bf16 v[84:87], v[168:171], v[200:203], v[84:87]
	v_mfma_f32_16x16x32_bf16 v[80:83], v[176:179], v[200:203], v[80:83]
	v_mfma_f32_16x16x32_bf16 v[68:71], v[168:171], v[208:211], v[68:71]
	v_mfma_f32_16x16x32_bf16 v[64:67], v[176:179], v[208:211], v[64:67]
	v_mfma_f32_16x16x32_bf16 v[116:119], v[172:175], v[188:191], v[116:119]
	v_mfma_f32_16x16x32_bf16 v[112:115], v[180:183], v[188:191], v[112:115]
	v_mfma_f32_16x16x32_bf16 v[100:103], v[172:175], v[196:199], v[100:103]
	v_mfma_f32_16x16x32_bf16 v[96:99], v[180:183], v[196:199], v[96:99]
	v_mfma_f32_16x16x32_bf16 v[84:87], v[172:175], v[204:207], v[84:87]
	v_mfma_f32_16x16x32_bf16 v[80:83], v[180:183], v[204:207], v[80:83]
	v_mfma_f32_16x16x32_bf16 v[68:71], v[172:175], v[212:215], v[68:71]
	v_mfma_f32_16x16x32_bf16 v[64:67], v[180:183], v[212:215], v[64:67]
	s_barrier
	s_setprio 0
	s_add_i32 s64, s51, s35
	v_lshl_add_u64 v[216:217], s[40:41], 0, v[130:131]
	s_mov_b32 m0, s64
	ds_read_b128 v[184:187], v150 offset:16384
	ds_read_b128 v[188:191], v150 offset:17408
	ds_read_b128 v[192:195], v150 offset:18432
	ds_read_b128 v[196:199], v150 offset:19456
	ds_read_b128 v[200:203], v150 offset:20480
	ds_read_b128 v[204:207], v150 offset:21504
	ds_read_b128 v[208:211], v150 offset:22528
	ds_read_b128 v[212:215], v150 offset:23552
	global_load_lds_dwordx4 v[216:217], off
	s_add_i32 m0, s64, 0x2000
	s_add_u32 s64, s40, 0x100000
	v_lshl_add_u64 v[218:219], s[40:41], 0, v[134:135]
	s_addc_u32 s65, s41, 0
	s_add_i32 s66, s56, s35
	global_load_lds_dwordx4 v[218:219], off
	v_lshl_add_u64 v[220:221], s[64:65], 0, v[130:131]
	s_mov_b32 m0, s66
	s_nop 0
	global_load_lds_dwordx4 v[220:221], off
	v_lshl_add_u64 v[220:221], s[64:65], 0, v[134:135]
	s_add_i32 m0, s66, 0x2000
	s_nop 0
	global_load_lds_dwordx4 v[220:221], off
	v_lshl_add_u64 v[220:221], s[42:43], 0, v[128:129]
	s_mov_b32 m0, s44
	s_nop 0
	global_load_lds_dwordx4 v[220:221], off
	v_lshl_add_u64 v[220:221], s[42:43], 0, v[132:133]
	s_mov_b32 m0, s45
	s_nop 0
	global_load_lds_dwordx4 v[220:221], off
	s_waitcnt vmcnt(8)
	s_waitcnt lgkmcnt(0)
	s_setprio 1
	s_barrier
	v_mfma_f32_16x16x32_bf16 v[60:63], v[152:155], v[184:187], v[60:63]
	v_mfma_f32_16x16x32_bf16 v[56:59], v[160:163], v[184:187], v[56:59]
	v_mfma_f32_16x16x32_bf16 v[44:47], v[152:155], v[192:195], v[44:47]
	v_mfma_f32_16x16x32_bf16 v[40:43], v[160:163], v[192:195], v[40:43]
	v_mfma_f32_16x16x32_bf16 v[28:31], v[152:155], v[200:203], v[28:31]
	v_mfma_f32_16x16x32_bf16 v[24:27], v[160:163], v[200:203], v[24:27]
	v_mfma_f32_16x16x32_bf16 v[12:15], v[152:155], v[208:211], v[12:15]
	v_mfma_f32_16x16x32_bf16 v[8:11], v[160:163], v[208:211], v[8:11]
	v_mfma_f32_16x16x32_bf16 v[60:63], v[156:159], v[188:191], v[60:63]
	v_mfma_f32_16x16x32_bf16 v[56:59], v[164:167], v[188:191], v[56:59]
	v_mfma_f32_16x16x32_bf16 v[44:47], v[156:159], v[196:199], v[44:47]
	v_mfma_f32_16x16x32_bf16 v[40:43], v[164:167], v[196:199], v[40:43]
	v_mfma_f32_16x16x32_bf16 v[28:31], v[156:159], v[204:207], v[28:31]
	v_mfma_f32_16x16x32_bf16 v[24:27], v[164:167], v[204:207], v[24:27]
	v_mfma_f32_16x16x32_bf16 v[12:15], v[156:159], v[212:215], v[12:15]
	v_mfma_f32_16x16x32_bf16 v[8:11], v[164:167], v[212:215], v[8:11]
	v_mfma_f32_16x16x32_bf16 v[52:55], v[168:171], v[184:187], v[52:55]
	v_mfma_f32_16x16x32_bf16 v[48:51], v[176:179], v[184:187], v[48:51]
	v_mfma_f32_16x16x32_bf16 v[36:39], v[168:171], v[192:195], v[36:39]
	v_mfma_f32_16x16x32_bf16 v[32:35], v[176:179], v[192:195], v[32:35]
	v_mfma_f32_16x16x32_bf16 v[20:23], v[168:171], v[200:203], v[20:23]
	v_mfma_f32_16x16x32_bf16 v[16:19], v[176:179], v[200:203], v[16:19]
	v_mfma_f32_16x16x32_bf16 v[4:7], v[168:171], v[208:211], v[4:7]
	v_mfma_f32_16x16x32_bf16 v[0:3], v[176:179], v[208:211], v[0:3]
	v_mfma_f32_16x16x32_bf16 v[52:55], v[172:175], v[188:191], v[52:55]
	v_mfma_f32_16x16x32_bf16 v[48:51], v[180:183], v[188:191], v[48:51]
	v_mfma_f32_16x16x32_bf16 v[36:39], v[172:175], v[196:199], v[36:39]
	v_mfma_f32_16x16x32_bf16 v[32:35], v[180:183], v[196:199], v[32:35]
	v_mfma_f32_16x16x32_bf16 v[20:23], v[172:175], v[204:207], v[20:23]
	v_mfma_f32_16x16x32_bf16 v[16:19], v[180:183], v[204:207], v[16:19]
	v_mfma_f32_16x16x32_bf16 v[4:7], v[172:175], v[212:215], v[4:7]
	v_mfma_f32_16x16x32_bf16 v[0:3], v[180:183], v[212:215], v[0:3]
	s_barrier
	s_setprio 0
	s_add_i32 s64, 0, 0x18000
	v_add_u32_e32 v151, s64, v149
	s_add_i32 s65, 0, 0x1c000
	ds_read_b128 v[152:155], v151
	ds_read_b128 v[156:159], v151 offset:1024
	ds_read_b128 v[160:163], v151 offset:2048
	ds_read_b128 v[164:167], v151 offset:3072
	v_add_u32_e32 v151, s65, v149
	ds_read_b128 v[168:171], v151
	ds_read_b128 v[172:175], v151 offset:1024
	ds_read_b128 v[176:179], v151 offset:2048
	ds_read_b128 v[180:183], v151 offset:3072
	s_add_u32 s42, s42, 0x2000
	s_addc_u32 s43, s43, 0
	s_mov_b32 m0, s46
	v_lshl_add_u64 v[220:221], s[42:43], 0, v[128:129]
	ds_read_b128 v[184:187], v150 offset:32768
	ds_read_b128 v[188:191], v150 offset:33792
	ds_read_b128 v[192:195], v150 offset:34816
	ds_read_b128 v[196:199], v150 offset:35840
	ds_read_b128 v[200:203], v150 offset:36864
	ds_read_b128 v[204:207], v150 offset:37888
	ds_read_b128 v[208:211], v150 offset:38912
	ds_read_b128 v[212:215], v150 offset:39936
	global_load_lds_dwordx4 v[220:221], off
	v_lshl_add_u64 v[220:221], s[42:43], 0, v[132:133]
	s_mov_b32 m0, s47
	s_nop 0
	global_load_lds_dwordx4 v[220:221], off
	s_waitcnt vmcnt(8)
	s_waitcnt lgkmcnt(0)
	s_setprio 1
	s_barrier
	v_mfma_f32_16x16x32_bf16 v[124:127], v[152:155], v[184:187], v[124:127]
	v_mfma_f32_16x16x32_bf16 v[120:123], v[160:163], v[184:187], v[120:123]
	v_mfma_f32_16x16x32_bf16 v[108:111], v[152:155], v[192:195], v[108:111]
	v_mfma_f32_16x16x32_bf16 v[104:107], v[160:163], v[192:195], v[104:107]
	v_mfma_f32_16x16x32_bf16 v[92:95], v[152:155], v[200:203], v[92:95]
	v_mfma_f32_16x16x32_bf16 v[88:91], v[160:163], v[200:203], v[88:91]
	v_mfma_f32_16x16x32_bf16 v[76:79], v[152:155], v[208:211], v[76:79]
	v_mfma_f32_16x16x32_bf16 v[72:75], v[160:163], v[208:211], v[72:75]
	v_mfma_f32_16x16x32_bf16 v[124:127], v[156:159], v[188:191], v[124:127]
	v_mfma_f32_16x16x32_bf16 v[120:123], v[164:167], v[188:191], v[120:123]
	v_mfma_f32_16x16x32_bf16 v[108:111], v[156:159], v[196:199], v[108:111]
	v_mfma_f32_16x16x32_bf16 v[104:107], v[164:167], v[196:199], v[104:107]
	v_mfma_f32_16x16x32_bf16 v[92:95], v[156:159], v[204:207], v[92:95]
	v_mfma_f32_16x16x32_bf16 v[88:91], v[164:167], v[204:207], v[88:91]
	v_mfma_f32_16x16x32_bf16 v[76:79], v[156:159], v[212:215], v[76:79]
	v_mfma_f32_16x16x32_bf16 v[72:75], v[164:167], v[212:215], v[72:75]
	v_mfma_f32_16x16x32_bf16 v[116:119], v[168:171], v[184:187], v[116:119]
	v_mfma_f32_16x16x32_bf16 v[112:115], v[176:179], v[184:187], v[112:115]
	v_mfma_f32_16x16x32_bf16 v[100:103], v[168:171], v[192:195], v[100:103]
	v_mfma_f32_16x16x32_bf16 v[96:99], v[176:179], v[192:195], v[96:99]
	v_mfma_f32_16x16x32_bf16 v[84:87], v[168:171], v[200:203], v[84:87]
	v_mfma_f32_16x16x32_bf16 v[80:83], v[176:179], v[200:203], v[80:83]
	v_mfma_f32_16x16x32_bf16 v[68:71], v[168:171], v[208:211], v[68:71]
	v_mfma_f32_16x16x32_bf16 v[64:67], v[176:179], v[208:211], v[64:67]
	v_mfma_f32_16x16x32_bf16 v[116:119], v[172:175], v[188:191], v[116:119]
	v_mfma_f32_16x16x32_bf16 v[112:115], v[180:183], v[188:191], v[112:115]
	v_mfma_f32_16x16x32_bf16 v[100:103], v[172:175], v[196:199], v[100:103]
	v_mfma_f32_16x16x32_bf16 v[96:99], v[180:183], v[196:199], v[96:99]
	v_mfma_f32_16x16x32_bf16 v[84:87], v[172:175], v[204:207], v[84:87]
	v_mfma_f32_16x16x32_bf16 v[80:83], v[180:183], v[204:207], v[80:83]
	v_mfma_f32_16x16x32_bf16 v[68:71], v[172:175], v[212:215], v[68:71]
	v_mfma_f32_16x16x32_bf16 v[64:67], v[180:183], v[212:215], v[64:67]
	s_barrier
	s_setprio 0
	s_add_i32 s42, s64, s35
	v_lshl_add_u64 v[216:217], v[216:217], 0, s[16:17]
	s_mov_b32 m0, s42
	ds_read_b128 v[184:187], v150 offset:49152
	ds_read_b128 v[188:191], v150 offset:50176
	ds_read_b128 v[192:195], v150 offset:51200
	ds_read_b128 v[196:199], v150 offset:52224
	ds_read_b128 v[200:203], v150 offset:53248
	ds_read_b128 v[204:207], v150 offset:54272
	ds_read_b128 v[208:211], v150 offset:55296
	ds_read_b128 v[212:215], v150 offset:56320
	global_load_lds_dwordx4 v[216:217], off
	s_add_i32 m0, s42, 0x2000
	s_add_u32 s40, s40, 0x100080
	v_lshl_add_u64 v[216:217], v[218:219], 0, s[16:17]
	s_addc_u32 s41, s41, 0
	s_add_i32 s42, s65, s35
	global_load_lds_dwordx4 v[216:217], off
	v_lshl_add_u64 v[216:217], s[40:41], 0, v[130:131]
	s_mov_b32 m0, s42
	s_nop 0
	global_load_lds_dwordx4 v[216:217], off
	v_lshl_add_u64 v[216:217], s[40:41], 0, v[134:135]
	s_add_i32 m0, s42, 0x2000
	s_nop 0
	global_load_lds_dwordx4 v[216:217], off
	v_lshl_add_u64 v[216:217], s[38:39], 0, v[128:129]
	s_mov_b32 m0, s48
	s_nop 0
	global_load_lds_dwordx4 v[216:217], off
	v_lshl_add_u64 v[216:217], s[38:39], 0, v[132:133]
	s_mov_b32 m0, s49
	s_nop 0
	global_load_lds_dwordx4 v[216:217], off
	s_waitcnt vmcnt(8)
	s_waitcnt lgkmcnt(0)
	s_setprio 1
	s_barrier
	v_mfma_f32_16x16x32_bf16 v[60:63], v[152:155], v[184:187], v[60:63]
	v_mfma_f32_16x16x32_bf16 v[56:59], v[160:163], v[184:187], v[56:59]
	v_mfma_f32_16x16x32_bf16 v[44:47], v[152:155], v[192:195], v[44:47]
	v_mfma_f32_16x16x32_bf16 v[40:43], v[160:163], v[192:195], v[40:43]
	v_mfma_f32_16x16x32_bf16 v[28:31], v[152:155], v[200:203], v[28:31]
	v_mfma_f32_16x16x32_bf16 v[24:27], v[160:163], v[200:203], v[24:27]
	v_mfma_f32_16x16x32_bf16 v[12:15], v[152:155], v[208:211], v[12:15]
	v_mfma_f32_16x16x32_bf16 v[8:11], v[160:163], v[208:211], v[8:11]
	v_mfma_f32_16x16x32_bf16 v[60:63], v[156:159], v[188:191], v[60:63]
	v_mfma_f32_16x16x32_bf16 v[56:59], v[164:167], v[188:191], v[56:59]
	v_mfma_f32_16x16x32_bf16 v[44:47], v[156:159], v[196:199], v[44:47]
	v_mfma_f32_16x16x32_bf16 v[40:43], v[164:167], v[196:199], v[40:43]
	v_mfma_f32_16x16x32_bf16 v[28:31], v[156:159], v[204:207], v[28:31]
	v_mfma_f32_16x16x32_bf16 v[24:27], v[164:167], v[204:207], v[24:27]
	v_mfma_f32_16x16x32_bf16 v[12:15], v[156:159], v[212:215], v[12:15]
	v_mfma_f32_16x16x32_bf16 v[8:11], v[164:167], v[212:215], v[8:11]
	v_mfma_f32_16x16x32_bf16 v[52:55], v[168:171], v[184:187], v[52:55]
	v_mfma_f32_16x16x32_bf16 v[48:51], v[176:179], v[184:187], v[48:51]
	v_mfma_f32_16x16x32_bf16 v[36:39], v[168:171], v[192:195], v[36:39]
	v_mfma_f32_16x16x32_bf16 v[32:35], v[176:179], v[192:195], v[32:35]
	v_mfma_f32_16x16x32_bf16 v[20:23], v[168:171], v[200:203], v[20:23]
	v_mfma_f32_16x16x32_bf16 v[16:19], v[176:179], v[200:203], v[16:19]
	v_mfma_f32_16x16x32_bf16 v[4:7], v[168:171], v[208:211], v[4:7]
	v_mfma_f32_16x16x32_bf16 v[0:3], v[176:179], v[208:211], v[0:3]
	v_mfma_f32_16x16x32_bf16 v[52:55], v[172:175], v[188:191], v[52:55]
	v_mfma_f32_16x16x32_bf16 v[48:51], v[180:183], v[188:191], v[48:51]
	v_mfma_f32_16x16x32_bf16 v[36:39], v[172:175], v[196:199], v[36:39]
	v_mfma_f32_16x16x32_bf16 v[32:35], v[180:183], v[196:199], v[32:35]
	v_mfma_f32_16x16x32_bf16 v[20:23], v[172:175], v[204:207], v[20:23]
	v_mfma_f32_16x16x32_bf16 v[16:19], v[180:183], v[204:207], v[16:19]
	v_mfma_f32_16x16x32_bf16 v[4:7], v[172:175], v[212:215], v[4:7]
	v_mfma_f32_16x16x32_bf16 v[0:3], v[180:183], v[212:215], v[0:3]
	s_barrier
	s_setprio 0
	s_add_i32 s63, s63, 2
	s_add_u32 s61, s61, 0x100
	s_addc_u32 s62, s62, 0
	s_add_u32 s36, s36, 0x10000
	s_addc_u32 s37, s37, 0
	v_lshl_add_u64 v[146:147], v[146:147], 0, s[18:19]
	s_cmp_gt_u32 s63, 61
	v_lshl_add_u64 v[144:145], v[144:145], 0, s[18:19]
	s_cbranch_scc0 .LBB0_615
	s_andn2_b64 vcc, exec, s[4:5]
	s_cbranch_vccnz .LBB0_607
	v_mov_b32_e32 v0, 0
	s_mov_b32 s8, s20
	s_mov_b32 s6, s22
	s_mov_b64 s[10:11], s[28:29]
	s_mov_b64 s[12:13], s[26:27]
	s_mov_b32 s50, s57
	v_mov_b32_e32 v1, v0
	v_mov_b32_e32 v2, v0
	v_mov_b32_e32 v3, v0
	v_mov_b32_e32 v4, v0
	v_mov_b32_e32 v5, v0
	v_mov_b32_e32 v6, v0
	v_mov_b32_e32 v7, v0
	v_mov_b32_e32 v16, v0
	v_mov_b32_e32 v17, v0
	v_mov_b32_e32 v18, v0
	v_mov_b32_e32 v19, v0
	v_mov_b32_e32 v20, v0
	v_mov_b32_e32 v21, v0
	v_mov_b32_e32 v22, v0
	v_mov_b32_e32 v23, v0
	v_mov_b32_e32 v32, v0
	v_mov_b32_e32 v33, v0
	v_mov_b32_e32 v34, v0
	v_mov_b32_e32 v35, v0
	v_mov_b32_e32 v36, v0
	v_mov_b32_e32 v37, v0
	v_mov_b32_e32 v38, v0
	v_mov_b32_e32 v39, v0
	v_mov_b32_e32 v48, v0
	v_mov_b32_e32 v49, v0
	v_mov_b32_e32 v50, v0
	v_mov_b32_e32 v51, v0
	v_mov_b32_e32 v52, v0
	v_mov_b32_e32 v53, v0
	v_mov_b32_e32 v54, v0
	v_mov_b32_e32 v55, v0
	v_mov_b32_e32 v8, v0
	v_mov_b32_e32 v9, v0
	v_mov_b32_e32 v10, v0
	v_mov_b32_e32 v11, v0
	v_mov_b32_e32 v12, v0
	v_mov_b32_e32 v13, v0
	v_mov_b32_e32 v14, v0
	v_mov_b32_e32 v15, v0
	v_mov_b32_e32 v24, v0
	v_mov_b32_e32 v25, v0
	v_mov_b32_e32 v26, v0
	v_mov_b32_e32 v27, v0
	v_mov_b32_e32 v28, v0
	v_mov_b32_e32 v29, v0
	v_mov_b32_e32 v30, v0
	v_mov_b32_e32 v31, v0
	v_mov_b32_e32 v40, v0
	v_mov_b32_e32 v41, v0
	v_mov_b32_e32 v42, v0
	v_mov_b32_e32 v43, v0
	v_mov_b32_e32 v44, v0
	v_mov_b32_e32 v45, v0
	v_mov_b32_e32 v46, v0
	v_mov_b32_e32 v47, v0
	v_mov_b32_e32 v56, v0
	v_mov_b32_e32 v57, v0
	v_mov_b32_e32 v58, v0
	v_mov_b32_e32 v59, v0
	v_mov_b32_e32 v60, v0
	v_mov_b32_e32 v61, v0
	v_mov_b32_e32 v62, v0
	v_mov_b32_e32 v63, v0
	v_mov_b32_e32 v64, v0
	v_mov_b32_e32 v65, v0
	v_mov_b32_e32 v66, v0
	v_mov_b32_e32 v67, v0
	v_mov_b32_e32 v68, v0
	v_mov_b32_e32 v69, v0
	v_mov_b32_e32 v70, v0
	v_mov_b32_e32 v71, v0
	v_mov_b32_e32 v80, v0
	v_mov_b32_e32 v81, v0
	v_mov_b32_e32 v82, v0
	v_mov_b32_e32 v83, v0
	v_mov_b32_e32 v84, v0
	v_mov_b32_e32 v85, v0
	v_mov_b32_e32 v86, v0
	v_mov_b32_e32 v87, v0
	v_mov_b32_e32 v96, v0
	v_mov_b32_e32 v97, v0
	v_mov_b32_e32 v98, v0
	v_mov_b32_e32 v99, v0
	v_mov_b32_e32 v100, v0
	v_mov_b32_e32 v101, v0
	v_mov_b32_e32 v102, v0
	v_mov_b32_e32 v103, v0
	v_mov_b32_e32 v112, v0
	v_mov_b32_e32 v113, v0
	v_mov_b32_e32 v114, v0
	v_mov_b32_e32 v115, v0
	v_mov_b32_e32 v116, v0
	v_mov_b32_e32 v117, v0
	v_mov_b32_e32 v118, v0
	v_mov_b32_e32 v119, v0
	v_mov_b32_e32 v72, v0
	v_mov_b32_e32 v73, v0
	v_mov_b32_e32 v74, v0
	v_mov_b32_e32 v75, v0
	v_mov_b32_e32 v76, v0
	v_mov_b32_e32 v77, v0
	v_mov_b32_e32 v78, v0
	v_mov_b32_e32 v79, v0
	v_mov_b32_e32 v88, v0
	v_mov_b32_e32 v89, v0
	v_mov_b32_e32 v90, v0
	v_mov_b32_e32 v91, v0
	v_mov_b32_e32 v92, v0
	v_mov_b32_e32 v93, v0
	v_mov_b32_e32 v94, v0
	v_mov_b32_e32 v95, v0
	v_mov_b32_e32 v104, v0
	v_mov_b32_e32 v105, v0
	v_mov_b32_e32 v106, v0
	v_mov_b32_e32 v107, v0
	v_mov_b32_e32 v108, v0
	v_mov_b32_e32 v109, v0
	v_mov_b32_e32 v110, v0
	v_mov_b32_e32 v111, v0
	v_mov_b32_e32 v120, v0
	v_mov_b32_e32 v121, v0
	v_mov_b32_e32 v122, v0
	v_mov_b32_e32 v123, v0
	v_mov_b32_e32 v124, v0
	v_mov_b32_e32 v125, v0
	v_mov_b32_e32 v126, v0
	v_mov_b32_e32 v127, v0
	s_branch .LBB0_607
